# code placement: 64-byte alignment (s_nop fill) of the four hot loop heads (attention loop, mem-unit loop, both GEMM k-loops)
# speedup vs baseline: 1.0009x; 1.0009x over previous
; template <class Epi, class Sched, bool ALIGN_EPI = false, bool SP2 = false>
; __device__ __forceinline__ void gemm_phase(PG8_LAS unsigned char* lds, const Gemm g, const Sched& S, const Epi& E, int wv) {
;     ...
;     for (;;) {
;         const bool has_next = S.next(ui + 1, nxt);
;         const char* nA = has_next ? (const char*)g.A + (size_t)nxt.pm * tstep : cA; const char* nB = has_next ? (const char*)g.Bt + (size_t)nxt.pn * tstep : cB;
;         for (int t = 0; t < nt; t += 2) {
;             const bool last = (t == nt - 2);
;             const char* a1 = cA + (size_t)(t + 1) * kstep;
;             const char* a2 = last ? nA : cA + (size_t)(t + 2) * kstep; const char* b2 = last ? nB : cB + (size_t)(t + 2) * kstep;
;     ...
; #pragma unroll
;         for (int a = 0; a < 2; ++a)
; #pragma unroll
;             for (int b = 0; b < 2; ++b)
; #pragma unroll
;                 for (int m = 0; m < 4; ++m)
; #pragma unroll
;                     for (int n = 0; n < 2; ++n) acc[a][b][m][n] = (f32x4){0.f, 0.f, 0.f, 0.f};
;         cur = nxt; cA = nA; cB = nB; ++ui;
.LBB0_119:
	s_ashr_i32 s21, s20, 31
	s_lshl_b64 s[38:39], s[20:21], 20
	s_add_u32 s38, s64, s38
	s_addc_u32 s39, s65, s39
	s_and_b64 s[40:41], s[36:37], exec
	s_cselect_b32 s7, s39, s35
	s_cselect_b32 s21, s38, s34
	s_ashr_i32 s19, s18, 31
	s_lshl_b64 s[40:41], s[18:19], 20
	s_add_u32 s40, s1, s40
	s_addc_u32 s41, s2, s41
	s_and_b64 s[46:47], s[36:37], exec
	s_cselect_b32 s19, s41, s45
	s_cselect_b32 s48, s40, s44
	s_add_u32 s34, s34, 0x80080
	s_addc_u32 s35, s35, 0
	s_add_u32 s49, s44, 0x100
	v_mov_b32_e32 v0, 0
	s_addc_u32 s50, s45, 0
	s_mov_b32 s51, -2
	v_mov_b32_e32 v1, v0
	v_mov_b32_e32 v2, v0
	v_mov_b32_e32 v3, v0
	v_mov_b32_e32 v4, v0
	v_mov_b32_e32 v5, v0
	v_mov_b32_e32 v6, v0
	v_mov_b32_e32 v7, v0
	v_mov_b32_e32 v12, v0
	v_mov_b32_e32 v13, v0
	v_mov_b32_e32 v14, v0
	v_mov_b32_e32 v15, v0
	v_mov_b32_e32 v20, v0
	v_mov_b32_e32 v21, v0
	v_mov_b32_e32 v22, v0
	v_mov_b32_e32 v23, v0
	v_mov_b32_e32 v28, v0
	v_mov_b32_e32 v29, v0
	v_mov_b32_e32 v30, v0
	v_mov_b32_e32 v31, v0
	v_mov_b32_e32 v36, v0
	v_mov_b32_e32 v37, v0
	v_mov_b32_e32 v38, v0
	v_mov_b32_e32 v39, v0
	v_mov_b32_e32 v44, v0
	v_mov_b32_e32 v45, v0
	v_mov_b32_e32 v46, v0
	v_mov_b32_e32 v47, v0
	v_mov_b32_e32 v52, v0
	v_mov_b32_e32 v53, v0
	v_mov_b32_e32 v54, v0
	v_mov_b32_e32 v55, v0
	v_mov_b32_e32 v8, v0
	v_mov_b32_e32 v9, v0
	v_mov_b32_e32 v10, v0
	v_mov_b32_e32 v11, v0
	v_mov_b32_e32 v16, v0
	v_mov_b32_e32 v17, v0
	v_mov_b32_e32 v18, v0
	v_mov_b32_e32 v19, v0
	v_mov_b32_e32 v24, v0
	v_mov_b32_e32 v25, v0
	v_mov_b32_e32 v26, v0
	v_mov_b32_e32 v27, v0
	v_mov_b32_e32 v32, v0
	v_mov_b32_e32 v33, v0
	v_mov_b32_e32 v34, v0
	v_mov_b32_e32 v35, v0
	v_mov_b32_e32 v40, v0
	v_mov_b32_e32 v41, v0
	v_mov_b32_e32 v42, v0
	v_mov_b32_e32 v43, v0
	v_mov_b32_e32 v48, v0
	v_mov_b32_e32 v49, v0
	v_mov_b32_e32 v50, v0
	v_mov_b32_e32 v51, v0
	v_mov_b32_e32 v56, v0
	v_mov_b32_e32 v57, v0
	v_mov_b32_e32 v58, v0
	v_mov_b32_e32 v59, v0
	v_mov_b32_e32 v60, v0
	v_mov_b32_e32 v61, v0
	v_mov_b32_e32 v62, v0
	v_mov_b32_e32 v63, v0
	v_mov_b32_e32 v64, v0
	v_mov_b32_e32 v65, v0
	v_mov_b32_e32 v66, v0
	v_mov_b32_e32 v67, v0
	v_mov_b32_e32 v68, v0
	v_mov_b32_e32 v69, v0
	v_mov_b32_e32 v70, v0
	v_mov_b32_e32 v71, v0
	v_mov_b32_e32 v76, v0
	v_mov_b32_e32 v77, v0
	v_mov_b32_e32 v78, v0
	v_mov_b32_e32 v79, v0
	v_mov_b32_e32 v84, v0
	v_mov_b32_e32 v85, v0
	v_mov_b32_e32 v86, v0
	v_mov_b32_e32 v87, v0
	v_mov_b32_e32 v92, v0
	v_mov_b32_e32 v93, v0
	v_mov_b32_e32 v94, v0
	v_mov_b32_e32 v95, v0
	v_mov_b32_e32 v100, v0
	v_mov_b32_e32 v101, v0
	v_mov_b32_e32 v102, v0
	v_mov_b32_e32 v103, v0
	v_mov_b32_e32 v108, v0
	v_mov_b32_e32 v109, v0
	v_mov_b32_e32 v110, v0
	v_mov_b32_e32 v111, v0
	v_mov_b32_e32 v116, v0
	v_mov_b32_e32 v117, v0
	v_mov_b32_e32 v118, v0
	v_mov_b32_e32 v119, v0
	v_mov_b32_e32 v72, v0
	v_mov_b32_e32 v73, v0
	v_mov_b32_e32 v74, v0
	v_mov_b32_e32 v75, v0
	v_mov_b32_e32 v80, v0
	v_mov_b32_e32 v81, v0
	v_mov_b32_e32 v82, v0
	v_mov_b32_e32 v83, v0
	v_mov_b32_e32 v88, v0
	v_mov_b32_e32 v89, v0
	v_mov_b32_e32 v90, v0
	v_mov_b32_e32 v91, v0
	v_mov_b32_e32 v96, v0
	v_mov_b32_e32 v97, v0
	v_mov_b32_e32 v98, v0
	v_mov_b32_e32 v99, v0
	v_mov_b32_e32 v104, v0
	v_mov_b32_e32 v105, v0
	v_mov_b32_e32 v106, v0
	v_mov_b32_e32 v107, v0
	v_mov_b32_e32 v112, v0
	v_mov_b32_e32 v113, v0
	v_mov_b32_e32 v114, v0
	v_mov_b32_e32 v115, v0
	v_mov_b32_e32 v120, v0
	v_mov_b32_e32 v121, v0
	v_mov_b32_e32 v122, v0
	v_mov_b32_e32 v123, v0
	v_mov_b32_e32 v124, v0
	v_mov_b32_e32 v125, v0
	v_mov_b32_e32 v126, v0
	v_mov_b32_e32 v127, v0
	.p2alignl 6, 3212836864

; __device__ __forceinline__ float bf2f(unsigned short h) { return __uint_as_float(((unsigned)h) << 16); }
; __device__ __forceinline__ void mem_unit(const MemArgs& A, int unit, char* lds, int wv) {
;     const int tid = opaque_tid(wv), wid = __builtin_amdgcn_readfirstlane(tid >> 6), lane = tid & 63, r32 = lane & 31, hi = lane >> 5;
;     const int b = unit / (4 * 32), hm = (unit / 32) % 4, qb = unit % 32;
;     const bf16* Kh = A.mkv + (size_t)b * NMEM * MKVC + A.layer * 1024 + hm * 128;
;     const bf16* Vh = Kh + 512;
;     char* V_lds = lds; char* K_lds = lds + 4 * SHM_V;
;     float* wsl = (float*)(lds + 131072) + wid * 64;
;     float nM2;
;     { const float a = wave_max(fmaxf(fabsf(A.gmq[lane]), fabsf(A.gmq[lane + 64]))), bb = wave_max(fmaxf(fabsf(A.gmk[lane]), fabsf(A.gmk[lane + 64])));
;       nM2 = -(11.3137085f * a * bb * LOG2E * 1.03f + 0.25f); }
;     { const int sr = tid >> 4, sc = (tid & 15) * 8, kc = sc * 2;
;       const f32x4 g0 = *(const f32x4*)(A.gmk + sc), g1 = *(const f32x4*)(A.gmk + sc + 4);
; #pragma unroll
;       for (int t = 0; t < 4; ++t)
; #pragma unroll
;         for (int hh = 0; hh < 2; ++hh) { const int key = t * 64 + hh * 32 + sr;
;           const bf16x8 v8 = *reinterpret_cast<const bf16x8*>(&Vh[(size_t)key * MKVC + sc]); const bf16x8 k8 = *reinterpret_cast<const bf16x8*>(&Kh[(size_t)key * MKVC + sc]);
;           float f[8]; float ss = 0.f;
; #pragma unroll
;           for (int i = 0; i < 8; ++i) { f[i] = bf2f((unsigned short)k8[i]); ss += f[i] * f[i]; }
;           ss += swz_xor<1>(ss); ss += swz_xor<2>(ss); ss += swz_xor<4>(ss); ss += swz_xor<8>(ss);
;           const float rn = 1.0f / sqrtf(ss * (1.0f / 128.0f) + EPS);
;           u32x4 w; w.x = cvtpk(f[0] * rn * g0.x, f[1] * rn * g0.y); w.y = cvtpk(f[2] * rn * g0.z, f[3] * rn * g0.w); w.z = cvtpk(f[4] * rn * g1.x, f[5] * rn * g1.y); w.w = cvtpk(f[6] * rn * g1.z, f[7] * rn * g1.w);
;           *(u32x4*)(K_lds + t * SHM_K + KSWZ(hh * 32 + sr, kc)) = w;
;           { const int ks_ = hh * 32 + sr, kp_ = (ks_ & ~0xC) | ((ks_ & 4) << 1) | ((ks_ & 8) >> 1);
;             *(bf16x8*)(V_lds + t * SHM_V + v_st(kp_, sc)) = v8; } } }
; __global__ void __launch_bounds__(512) fwd_megakernel(Args args) {
;     ...
;             for (int first_ = 1;; first_ = 0) { const int it = first_ ? bx : att::next_item(ctr, (char*)lds, opaque_tid(wave));
;                 if (it >= 768 + 256 + 256) break;
.LBB0_196:
	s_cmpk_gt_i32 s20, 0x4ff
	s_mov_b64 s[6:7], -1
	s_cbranch_scc1 .LBB0_195
	s_cmpk_gt_i32 s20, 0x2ff
	s_cbranch_scc0 .LBB0_213
	s_cmpk_gt_u32 s20, 0x3ff
	s_cbranch_scc0 .LBB0_204
	s_add_i32 s3, s20, 0xfffffc00
	v_mbcnt_lo_u32_b32 v78, -1, 0
	v_mbcnt_hi_u32_b32 v78, -1, v78
	v_readlane_b32 s16, v255, 0
	v_and_b32_e32 v145, 63, v78
	s_lshr_b32 s84, s3, 7
	v_lshlrev_b32_e32 v0, 2, v145
	v_readlane_b32 s17, v255, 1
	s_lshl_b64 s[0:1], s[84:85], 21
	v_readlane_b32 s2, v255, 4
	global_load_dword v6, v0, s[40:41]
	global_load_dword v7, v0, s[40:41] offset:256
	s_nop 0
	global_load_dword v8, v0, s[16:17]
	global_load_dword v9, v0, s[16:17] offset:256
	s_add_u32 s2, s2, s0
	v_readlane_b32 s0, v255, 5
	v_add_u32_e32 v40, s44, v78
	s_addc_u32 s1, s0, s1
	s_lshl_b32 s0, s3, 2
	s_and_b32 s0, s0, 0x180
	v_ashrrev_i32_e32 v28, 4, v40
	v_lshlrev_b32_e32 v16, 3, v78
	s_lshl_b32 s6, s0, 1
	v_and_b32_e32 v17, 0x78, v16
	v_ashrrev_i32_e32 v29, 31, v28
	s_add_u32 s8, s2, s6
	v_lshlrev_b32_e32 v18, 1, v17
	v_lshlrev_b64 v[0:1], 13, v[28:29]
	s_addc_u32 s9, s1, 0
	v_or_b32_e32 v0, v0, v18
	v_lshl_add_u64 v[24:25], s[8:9], 0, v[0:1]
	global_load_dwordx4 v[0:3], v[24:25], off
	v_add_u32_e32 v26, 32, v28
	v_ashrrev_i32_e32 v27, 31, v26
	v_lshlrev_b64 v[4:5], 13, v[26:27]
	v_or_b32_e32 v4, v4, v18
	v_lshl_add_u64 v[4:5], s[8:9], 0, v[4:5]
	v_and_b32_e32 v19, 0xf0, v40
	s_add_i32 s2, 0, 0x10000
	v_xad_u32 v56, v18, v19, s2
	s_mov_b32 s18, 0xf800000
	v_bfe_u32 v57, v16, 5, 2
	v_lshlrev_b32_e32 v16, 6, v28
	v_and_b32_e32 v16, 0x1c0, v16
	v_readfirstlane_b32 s1, v40
	s_lshl_b32 s3, s3, 8
	s_and_b32 s3, s3, 0x1f00
	v_and_b32_e32 v144, 31, v78
	s_mov_b32 s7, s85
	v_bfe_u32 v146, v78, 5, 1
	v_lshlrev_b32_e32 v176, 4, v146
	v_and_b32_e32 v108, 32, v78
	s_mov_b32 s2, 0
	s_waitcnt vmcnt(4)
	v_max_f32_e64 v6, |v6|, |v6|
	s_waitcnt vmcnt(3)
	v_max_f32_e64 v7, |v7|, |v7|
	s_waitcnt vmcnt(1)
	v_max_f32_e64 v9, |v9|, |v9|
	v_max_f32_e64 v8, |v8|, |v8|
	v_max_f32_e32 v6, v6, v7
	v_max_f32_e32 v7, v8, v9
	ds_swizzle_b32 v27, v6 offset:swizzle(SWAP,1)
	ds_swizzle_b32 v29, v7 offset:swizzle(SWAP,1)
	global_load_dwordx4 v[12:15], v[24:25], off offset:1024
	global_load_dwordx4 v[8:11], v[4:5], off offset:1024
	global_load_dwordx4 v[20:23], v[4:5], off
	s_waitcnt lgkmcnt(1)
	v_max_f32_e32 v4, v27, v27
	s_waitcnt lgkmcnt(0)
	v_max_f32_e32 v5, v29, v29
	v_max_f32_e32 v27, v6, v4
	v_max_f32_e32 v29, v7, v5
	ds_swizzle_b32 v38, v27 offset:swizzle(SWAP,2)
	ds_swizzle_b32 v39, v29 offset:swizzle(SWAP,2)
	s_waitcnt vmcnt(3)
	v_and_b32_e32 v37, 0xffff0000, v0
	v_lshlrev_b32_e32 v36, 16, v0
	v_and_b32_e32 v35, 0xffff0000, v1
	v_lshlrev_b32_e32 v34, 16, v1
	v_pk_mul_f32 v[6:7], v[36:37], v[36:37]
	v_pk_mul_f32 v[4:5], v[34:35], v[34:35]
	v_add_f32_e32 v6, v6, v7
	v_and_b32_e32 v33, 0xffff0000, v2
	v_lshlrev_b32_e32 v32, 16, v2
	v_add_f32_e32 v4, v4, v6
	v_and_b32_e32 v31, 0xffff0000, v3
	v_lshlrev_b32_e32 v30, 16, v3
	v_pk_mul_f32 v[2:3], v[32:33], v[32:33]
	v_add_f32_e32 v4, v5, v4
	v_add_f32_e32 v2, v2, v4
	v_pk_mul_f32 v[0:1], v[30:31], v[30:31]
	v_add_f32_e32 v2, v3, v2
	s_waitcnt lgkmcnt(1)
	v_max_f32_e32 v3, v38, v38
	s_waitcnt lgkmcnt(0)
	v_max_f32_e32 v4, v39, v39
	v_add_f32_e32 v0, v0, v2
	v_max_f32_e32 v2, v27, v3
	v_max_f32_e32 v3, v29, v4
	v_add_f32_e32 v0, v1, v0
	ds_swizzle_b32 v1, v2 offset:swizzle(SWAP,4)
	ds_swizzle_b32 v4, v3 offset:swizzle(SWAP,4)
	ds_swizzle_b32 v5, v0 offset:swizzle(SWAP,1)
	v_lshlrev_b32_e32 v6, 2, v17
	v_and_b32_e32 v27, 8, v28
	s_waitcnt lgkmcnt(2)
	v_max_f32_e32 v1, v1, v1
	s_waitcnt lgkmcnt(1)
	v_max_f32_e32 v4, v4, v4
	s_waitcnt lgkmcnt(0)
	v_add_f32_e32 v17, v0, v5
	v_max_f32_e32 v29, v2, v1
	v_max_f32_e32 v38, v3, v4
	global_load_dwordx4 v[0:3], v6, s[16:17] offset:16
	s_nop 0
	global_load_dwordx4 v[4:7], v6, s[16:17]
	s_mov_b32 s100, 0x80000
	s_mov_b32 s101, 0
	v_lshl_add_u64 v[80:81], v[24:25], 0, s[100:101]
	global_load_dwordx4 v[62:65], v[80:81], off offset:1024
	global_load_dwordx4 v[66:69], v[80:81], off
	s_mov_b32 s100, 0xc0000
	s_mov_b32 s101, 0
	v_lshl_add_u64 v[80:81], v[24:25], 0, s[100:101]
	global_load_dwordx4 v[70:73], v[80:81], off offset:1024
	global_load_dwordx4 v[74:77], v[80:81], off
	s_mov_b32 s100, 0x100000
	s_mov_b32 s101, 0
	v_lshl_add_u64 v[80:81], v[24:25], 0, s[100:101]
	global_load_dwordx4 v[112:115], v[80:81], off offset:1024
	global_load_dwordx4 v[116:119], v[80:81], off
	s_mov_b32 s100, 0x140000
	s_mov_b32 s101, 0
	v_lshl_add_u64 v[80:81], v[24:25], 0, s[100:101]
	global_load_dwordx4 v[120:123], v[80:81], off offset:1024
	global_load_dwordx4 v[124:127], v[80:81], off
	s_mov_b32 s100, 0x180000
	s_mov_b32 s101, 0
	v_lshl_add_u64 v[80:81], v[24:25], 0, s[100:101]
	global_load_dwordx4 v[128:131], v[80:81], off offset:1024
	global_load_dwordx4 v[132:135], v[80:81], off
	s_mov_b32 s100, 0x1c0000
	s_mov_b32 s101, 0
	v_lshl_add_u64 v[80:81], v[24:25], 0, s[100:101]
	global_load_dwordx4 v[136:139], v[80:81], off offset:1024
	global_load_dwordx4 v[140:143], v[80:81], off
	ds_swizzle_b32 v39, v17 offset:swizzle(SWAP,2)
	ds_swizzle_b32 v41, v29 offset:swizzle(SWAP,8)
	ds_swizzle_b32 v42, v38 offset:swizzle(SWAP,8)
	s_waitcnt lgkmcnt(2)
	v_add_f32_e32 v17, v17, v39
	s_waitcnt lgkmcnt(1)
	v_max_f32_e32 v39, v41, v41
	s_waitcnt lgkmcnt(0)
	v_max_f32_e32 v41, v42, v42
	ds_swizzle_b32 v42, v17 offset:swizzle(SWAP,4)
	v_max_f32_e32 v29, v29, v39
	v_max_f32_e32 v38, v38, v41
	ds_swizzle_b32 v39, v29 offset:swizzle(SWAP,16)
	ds_swizzle_b32 v41, v38 offset:swizzle(SWAP,16)
	s_waitcnt lgkmcnt(2)
	v_add_f32_e32 v17, v17, v42
	ds_swizzle_b32 v19, v17 offset:swizzle(SWAP,8)
	s_waitcnt lgkmcnt(2)
	v_max_f32_e32 v39, v39, v39
	s_waitcnt lgkmcnt(1)
; template <int X> __device__ __forceinline__ float swz_xor(float v) { return __int_as_float(__builtin_amdgcn_ds_swizzle(__float_as_int(v), (X << 10) | 0x1f)); }
; __device__ __forceinline__ unsigned cvtpk(float lo, float hi) { f32x2_t v = {lo, hi}; bf16x2_t b = __builtin_convertvector(v, bf16x2_t); return __builtin_bit_cast(unsigned, b); }
; __device__ __forceinline__ float bf2f(unsigned short h) { return __uint_as_float(((unsigned)h) << 16); }
; __device__ __forceinline__ float wave_max(float v) { v = fmaxf(v, swz_xor<1>(v)); v = fmaxf(v, swz_xor<2>(v)); v = fmaxf(v, swz_xor<4>(v)); v = fmaxf(v, swz_xor<8>(v)); v = fmaxf(v, swz_xor<16>(v)); return xmax32(v); }
; __device__ __forceinline__ void mem_unit(const MemArgs& A, int unit, char* lds, int wv) {
;     ...
;     { const float a = wave_max(fmaxf(fabsf(A.gmq[lane]), fabsf(A.gmq[lane + 64]))), bb = wave_max(fmaxf(fabsf(A.gmk[lane]), fabsf(A.gmk[lane + 64])));
;       nM2 = -(11.3137085f * a * bb * LOG2E * 1.03f + 0.25f); }
;     { const int sr = tid >> 4, sc = (tid & 15) * 8, kc = sc * 2;
;       const f32x4 g0 = *(const f32x4*)(A.gmk + sc), g1 = *(const f32x4*)(A.gmk + sc + 4);
; #pragma unroll
;       for (int t = 0; t < 4; ++t)
; #pragma unroll
;         for (int hh = 0; hh < 2; ++hh) { const int key = t * 64 + hh * 32 + sr;
;           const bf16x8 v8 = *reinterpret_cast<const bf16x8*>(&Vh[(size_t)key * MKVC + sc]); const bf16x8 k8 = *reinterpret_cast<const bf16x8*>(&Kh[(size_t)key * MKVC + sc]);
;           float f[8]; float ss = 0.f;
; #pragma unroll
;           for (int i = 0; i < 8; ++i) { f[i] = bf2f((unsigned short)k8[i]); ss += f[i] * f[i]; }
;           ss += swz_xor<1>(ss); ss += swz_xor<2>(ss); ss += swz_xor<4>(ss); ss += swz_xor<8>(ss);
;           const float rn = 1.0f / sqrtf(ss * (1.0f / 128.0f) + EPS);
;           u32x4 w; w.x = cvtpk(f[0] * rn * g0.x, f[1] * rn * g0.y); w.y = cvtpk(f[2] * rn * g0.z, f[3] * rn * g0.w); w.z = cvtpk(f[4] * rn * g1.x, f[5] * rn * g1.y); w.w = cvtpk(f[6] * rn * g1.z, f[7] * rn * g1.w);
;           *(u32x4*)(K_lds + t * SHM_K + KSWZ(hh * 32 + sr, kc)) = w;
;           { const int ks_ = hh * 32 + sr, kp_ = (ks_ & ~0xC) | ((ks_ & 4) << 1) | ((ks_ & 8) >> 1);
;             *(bf16x8*)(V_lds + t * SHM_V + v_st(kp_, sc)) = v8; } } }
	v_max_f32_e32 v41, v41, v41
	v_max_f32_e32 v29, v29, v39
	v_max_f32_e32 v38, v38, v41
	v_mov_b32_e32 v39, v29
	v_mov_b32_e32 v41, v38
	s_nop 0
	v_permlane32_swap_b32_e32 v29, v39
	v_permlane32_swap_b32_e32 v38, v41
	v_max_f32_e32 v39, v39, v39
	v_max_f32_e32 v29, v29, v29
	v_max_f32_e32 v41, v41, v41
	v_max_f32_e32 v38, v38, v38
	s_waitcnt lgkmcnt(0)
	v_add_f32_e32 v17, v17, v19
	v_max_f32_e32 v19, v29, v39
	v_max_f32_e32 v29, v38, v41
	v_fmamk_f32 v17, v17, 0x3c000000, v224
	v_mul_f32_e32 v19, 0x413504f3, v19
	v_mul_f32_e32 v38, 0x4f800000, v17
	v_mul_f32_e32 v19, v19, v29
	v_cmp_gt_f32_e32 vcc, s18, v17
	v_mul_f32_e32 v19, 0x3fb8aa3b, v19
	v_mov_b32_e32 v29, 0x3e800000
	v_cndmask_b32_e32 v17, v17, v38, vcc
	v_fmamk_f32 v79, v19, 0x3f83d70a, v29
	v_sqrt_f32_e32 v19, v17
	s_waitcnt vmcnt(14)
	v_and_b32_e32 v51, 0xffff0000, v21
	v_lshlrev_b32_e32 v50, 16, v21
	v_and_b32_e32 v21, 0xffff0000, v20
	v_add_u32_e32 v29, -1, v19
	v_fma_f32 v38, -v29, v19, v17
	v_cmp_ge_f32_e64 s[36:37], 0, v38
	v_add_u32_e32 v38, 1, v19
	v_lshlrev_b32_e32 v20, 16, v20
	v_cndmask_b32_e64 v29, v19, v29, s[36:37]
	v_fma_f32 v19, -v38, v19, v17
	v_cmp_lt_f32_e64 s[36:37], 0, v19
	v_pk_mul_f32 v[54:55], v[20:21], v[20:21]
	v_pk_mul_f32 v[52:53], v[50:51], v[50:51]
	v_cndmask_b32_e64 v19, v29, v38, s[36:37]
	v_mul_f32_e32 v29, 0x37800000, v19
	v_cndmask_b32_e32 v19, v19, v29, vcc
	v_cmp_class_f32_e32 vcc, v17, v250
	v_add_f32_e32 v54, v54, v55
	v_and_b32_e32 v39, 0xffff0000, v23
	v_cndmask_b32_e32 v29, v19, v17, vcc
	v_div_scale_f32 v41, s[8:9], v29, v29, 1.0
	v_rcp_f32_e32 v58, v41
	v_and_b32_e32 v17, 48, v18
	v_add3_u32 v59, 0, v16, v17
	v_div_scale_f32 v60, vcc, 1.0, v29, 1.0
	v_fma_f32 v16, -v41, v58, 1.0
	v_fmac_f32_e32 v58, v16, v58
	v_lshlrev_b32_e32 v38, 16, v23
	v_and_b32_e32 v23, 0xffff0000, v22
	v_lshlrev_b32_e32 v22, 16, v22
	v_add_f32_e32 v52, v52, v54
	v_mul_f32_e32 v61, v60, v58
	v_pk_mul_f32 v[48:49], v[22:23], v[22:23]
	v_add_f32_e32 v52, v53, v52
	v_fma_f32 v16, -v41, v61, v60
	s_mov_b64 s[8:9], 0x80000
	v_add_f32_e32 v48, v48, v52
	v_fmac_f32_e32 v61, v16, v58
	v_pk_mul_f32 v[46:47], v[38:39], v[38:39]
	v_lshl_add_u64 v[16:17], v[24:25], 0, s[8:9]
	s_mov_b32 s8, 0x80000
	v_add_f32_e32 v48, v49, v48
	v_add_co_u32_e64 v42, s[36:37], s8, v24
	v_add_f32_e32 v46, v46, v48
	s_nop 0
	v_addc_co_u32_e64 v43, s[36:37], 0, v25, s[36:37]
	v_add_f32_e32 v46, v47, v46
	s_waitcnt vmcnt(10)
	v_mov_b32_e32 v16, v62
	v_mov_b32_e32 v17, v63
	v_mov_b32_e32 v18, v64
	v_mov_b32_e32 v19, v65
	s_nop 0
	v_mov_b32_e32 v42, v66
	v_mov_b32_e32 v43, v67
	v_mov_b32_e32 v44, v68
	v_mov_b32_e32 v45, v69
	ds_swizzle_b32 v47, v46 offset:swizzle(SWAP,1)
	v_fma_f32 v41, -v41, v61, v60
	v_div_fmas_f32 v41, v41, v58, v61
	v_div_fixup_f32 v52, v41, v29, 1.0
	v_pk_mul_f32 v[36:37], v[52:53], v[36:37] op_sel_hi:[0,1]
	s_waitcnt lgkmcnt(0)
	v_add_f32_e32 v29, v46, v47
	ds_swizzle_b32 v41, v29 offset:swizzle(SWAP,2)
	s_nop 0
	v_pk_mul_f32 v[36:37], v[4:5], v[36:37]
	v_pk_mul_f32 v[34:35], v[52:53], v[34:35] op_sel_hi:[0,1]
	v_cvt_pk_bf16_f32 v46, v36, v37
	v_pk_mul_f32 v[34:35], v[6:7], v[34:35]
	s_waitcnt lgkmcnt(0)
	v_add_f32_e32 v29, v29, v41
	ds_swizzle_b32 v36, v29 offset:swizzle(SWAP,4)
	v_cvt_pk_bf16_f32 v47, v34, v35
	v_pk_mul_f32 v[30:31], v[52:53], v[30:31] op_sel_hi:[0,1]
	v_pk_mul_f32 v[30:31], v[2:3], v[30:31]
	v_pk_mul_f32 v[32:33], v[52:53], v[32:33] op_sel_hi:[0,1]
	s_waitcnt lgkmcnt(0)
	v_add_f32_e32 v29, v29, v36
	ds_swizzle_b32 v34, v29 offset:swizzle(SWAP,8)
	v_cvt_pk_bf16_f32 v49, v30, v31
	v_pk_mul_f32 v[32:33], v[0:1], v[32:33]
	s_waitcnt lgkmcnt(0)
	v_add_f32_e32 v29, v29, v34
	v_fmamk_f32 v29, v29, 0x3c000000, v224
	v_mul_f32_e32 v30, 0x4f800000, v29
	v_cmp_gt_f32_e32 vcc, s18, v29
	v_cvt_pk_bf16_f32 v48, v32, v33
	s_nop 0
	v_cndmask_b32_e32 v29, v29, v30, vcc
	v_sqrt_f32_e32 v31, v29
	v_lshl_add_u32 v30, v28, 8, v56
	v_lshrrev_b32_e32 v28, 5, v40
	ds_write_b128 v30, v[46:49]
	v_add_u32_e32 v32, -1, v31
	v_fma_f32 v33, -v32, v31, v29
	v_cmp_ge_f32_e64 s[36:37], 0, v33
	v_add_u32_e32 v33, 1, v31
	s_nop 0
	v_and_b32_e32 v47, 0xffff0000, v43
	v_cndmask_b32_e64 v32, v31, v32, s[36:37]
	v_fma_f32 v31, -v33, v31, v29
	v_cmp_lt_f32_e64 s[36:37], 0, v31
	v_lshlrev_b32_e32 v46, 16, v43
	v_and_b32_e32 v43, 0xffff0000, v42
	v_cndmask_b32_e64 v31, v32, v33, s[36:37]
	v_mul_f32_e32 v32, 0x37800000, v31
	v_cndmask_b32_e32 v31, v31, v32, vcc
	v_cmp_class_f32_e32 vcc, v29, v250
	v_lshlrev_b32_e32 v42, 16, v42
	v_pk_mul_f32 v[52:53], v[42:43], v[42:43]
	v_cndmask_b32_e32 v54, v31, v29, vcc
	v_div_scale_f32 v32, s[8:9], v54, v54, 1.0
	v_rcp_f32_e32 v55, v32
	s_mov_b32 s8, 0x7ffffc
	v_and_or_b32 v28, v28, s8, v57
	v_lshl_add_u32 v31, v28, 9, v59
	ds_write_b128 v31, v[12:15]
	v_fma_f32 v12, -v32, v55, 1.0
	v_fmac_f32_e32 v55, v12, v55
	v_div_scale_f32 v33, vcc, 1.0, v54, 1.0
	v_mul_f32_e32 v58, v33, v55
	v_fma_f32 v12, -v32, v58, v33
	s_mov_b64 s[8:9], 0xc0000
	v_fmac_f32_e32 v58, v12, v55
	v_lshl_add_u64 v[12:13], v[24:25], 0, s[8:9]
	s_mov_b32 s8, 0xc0000
	v_add_co_u32_e64 v28, s[36:37], s8, v24
	v_pk_mul_f32 v[48:49], v[46:47], v[46:47]
	s_nop 0
	v_addc_co_u32_e64 v29, s[36:37], 0, v25, s[36:37]
	s_waitcnt vmcnt(8)
	v_mov_b32_e32 v12, v70
	v_mov_b32_e32 v13, v71
	v_mov_b32_e32 v14, v72
	v_mov_b32_e32 v15, v73
	s_nop 0
	v_mov_b32_e32 v34, v74
	v_mov_b32_e32 v35, v75
	v_mov_b32_e32 v36, v76
	v_mov_b32_e32 v37, v77
	v_add_f32_e32 v52, v52, v53
	v_and_b32_e32 v29, 0xffff0000, v45
	v_lshlrev_b32_e32 v28, 16, v45
	v_and_b32_e32 v45, 0xffff0000, v44
	v_lshlrev_b32_e32 v44, 16, v44
	v_add_f32_e32 v48, v48, v52
	v_pk_mul_f32 v[40:41], v[44:45], v[44:45]
	v_add_f32_e32 v48, v49, v48
	v_add_f32_e32 v40, v40, v48
	v_fma_f32 v60, -v32, v58, v33
	v_pk_mul_f32 v[32:33], v[28:29], v[28:29]
	v_add_f32_e32 v40, v41, v40
	v_add_f32_e32 v32, v32, v40
	v_add_f32_e32 v33, v33, v32
	ds_swizzle_b32 v40, v33 offset:swizzle(SWAP,1)
	v_div_fmas_f32 v32, v60, v55, v58
	v_div_fixup_f32 v32, v32, v54, 1.0
	v_pk_mul_f32 v[20:21], v[32:33], v[20:21] op_sel_hi:[0,1]
	v_pk_mul_f32 v[20:21], v[4:5], v[20:21]
	s_waitcnt lgkmcnt(0)
; template <int X> __device__ __forceinline__ float swz_xor(float v) { return __int_as_float(__builtin_amdgcn_ds_swizzle(__float_as_int(v), (X << 10) | 0x1f)); }
; __device__ __forceinline__ unsigned cvtpk(float lo, float hi) { f32x2_t v = {lo, hi}; bf16x2_t b = __builtin_convertvector(v, bf16x2_t); return __builtin_bit_cast(unsigned, b); }
; __device__ __forceinline__ float bf2f(unsigned short h) { return __uint_as_float(((unsigned)h) << 16); }
; __device__ __forceinline__ int v_st(int k, int c) { const int kk = (k & ~0xC) | ((k & 4) << 1) | ((k & 8) >> 1); return ((kk >> 3) * 4 + (c >> 5)) * 512 + ((kk & 7) * 32 + (c & 31)) * 2; }
; __device__ __forceinline__ void mem_unit(const MemArgs& A, int unit, char* lds, int wv) {
;     ...
;         for (int hh = 0; hh < 2; ++hh) { const int key = t * 64 + hh * 32 + sr;
;           const bf16x8 v8 = *reinterpret_cast<const bf16x8*>(&Vh[(size_t)key * MKVC + sc]); const bf16x8 k8 = *reinterpret_cast<const bf16x8*>(&Kh[(size_t)key * MKVC + sc]);
;           float f[8]; float ss = 0.f;
; #pragma unroll
;           for (int i = 0; i < 8; ++i) { f[i] = bf2f((unsigned short)k8[i]); ss += f[i] * f[i]; }
;           ss += swz_xor<1>(ss); ss += swz_xor<2>(ss); ss += swz_xor<4>(ss); ss += swz_xor<8>(ss);
;           const float rn = 1.0f / sqrtf(ss * (1.0f / 128.0f) + EPS);
;           u32x4 w; w.x = cvtpk(f[0] * rn * g0.x, f[1] * rn * g0.y); w.y = cvtpk(f[2] * rn * g0.z, f[3] * rn * g0.w); w.z = cvtpk(f[4] * rn * g1.x, f[5] * rn * g1.y); w.w = cvtpk(f[6] * rn * g1.z, f[7] * rn * g1.w);
;           *(u32x4*)(K_lds + t * SHM_K + KSWZ(hh * 32 + sr, kc)) = w;
;           { const int ks_ = hh * 32 + sr, kp_ = (ks_ & ~0xC) | ((ks_ & 4) << 1) | ((ks_ & 8) >> 1);
;             *(bf16x8*)(V_lds + t * SHM_V + v_st(kp_, sc)) = v8; } } }
	v_add_f32_e32 v33, v33, v40
	ds_swizzle_b32 v48, v33 offset:swizzle(SWAP,2)
	v_pk_mul_f32 v[40:41], v[32:33], v[50:51] op_sel_hi:[0,1]
	v_pk_mul_f32 v[40:41], v[6:7], v[40:41]
	v_cvt_pk_bf16_f32 v20, v20, v21
	v_cvt_pk_bf16_f32 v21, v40, v41
	s_waitcnt lgkmcnt(0)
	v_add_f32_e32 v33, v33, v48
	ds_swizzle_b32 v48, v33 offset:swizzle(SWAP,4)
	v_pk_mul_f32 v[22:23], v[32:33], v[22:23] op_sel_hi:[0,1]
	v_pk_mul_f32 v[22:23], v[0:1], v[22:23]
	s_mov_b32 s8, 0xfffff0
	v_cvt_pk_bf16_f32 v22, v22, v23
	s_waitcnt lgkmcnt(0)
	v_add_f32_e32 v40, v33, v48
	ds_swizzle_b32 v41, v40 offset:swizzle(SWAP,8)
	v_pk_mul_f32 v[32:33], v[32:33], v[38:39] op_sel_hi:[0,1]
	v_pk_mul_f32 v[32:33], v[2:3], v[32:33]
	s_nop 0
	v_and_b32_e32 v55, 0xffff0000, v34
	v_cvt_pk_bf16_f32 v23, v32, v33
	s_waitcnt lgkmcnt(0)
	v_add_f32_e32 v33, v40, v41
	v_fmamk_f32 v33, v33, 0x3c000000, v224
	v_mul_f32_e32 v38, 0x4f800000, v33
	v_cmp_gt_f32_e32 vcc, s18, v33
	v_lshl_add_u32 v32, v26, 8, v56
	ds_write_b128 v32, v[20:23]
	v_cndmask_b32_e32 v33, v33, v38, vcc
	v_sqrt_f32_e32 v38, v33
	v_and_or_b32 v20, v26, s8, v27
	v_lshrrev_b32_e32 v48, 1, v20
	s_mov_b64 s[8:9], 0x100000
	v_add_u32_e32 v20, -1, v38
	v_fma_f32 v21, -v20, v38, v33
	v_cmp_ge_f32_e64 s[36:37], 0, v21
	v_add_u32_e32 v21, 1, v38
	v_fma_f32 v22, -v21, v38, v33
	v_cndmask_b32_e64 v20, v38, v20, s[36:37]
	v_cmp_lt_f32_e64 s[36:37], 0, v22
	v_lshlrev_b32_e32 v54, 16, v34
	v_and_b32_e32 v53, 0xffff0000, v35
	v_cndmask_b32_e64 v20, v20, v21, s[36:37]
	v_mul_f32_e32 v21, 0x37800000, v20
	v_cndmask_b32_e32 v20, v20, v21, vcc
	v_cmp_class_f32_e32 vcc, v33, v250
	v_lshlrev_b32_e32 v52, 16, v35
	v_pk_mul_f32 v[34:35], v[54:55], v[54:55]
	v_cndmask_b32_e32 v56, v20, v33, vcc
	v_lshl_add_u64 v[20:21], v[24:25], 0, s[8:9]
	s_mov_b32 s8, 0x100000
	v_add_co_u32_e32 v26, vcc, s8, v24
	v_div_scale_f32 v58, s[8:9], v56, v56, 1.0
	s_nop 0
	v_addc_co_u32_e32 v27, vcc, 0, v25, vcc
	s_waitcnt vmcnt(6)
	v_mov_b32_e32 v20, v112
	v_mov_b32_e32 v21, v113
	v_mov_b32_e32 v22, v114
	v_mov_b32_e32 v23, v115
	s_nop 0
	v_mov_b32_e32 v38, v116
	v_mov_b32_e32 v39, v117
	v_mov_b32_e32 v40, v118
	v_mov_b32_e32 v41, v119
	v_rcp_f32_e32 v60, v58
	v_or_b32_e32 v26, v48, v57
	v_lshl_add_u32 v33, v26, 9, v59
	v_pk_mul_f32 v[26:27], v[52:53], v[52:53]
	v_add_f32_e32 v34, v34, v35
	v_and_b32_e32 v51, 0xffff0000, v36
	v_lshlrev_b32_e32 v50, 16, v36
	v_add_f32_e32 v26, v26, v34
	ds_write_b128 v33, v[8:11]
	v_pk_mul_f32 v[10:11], v[50:51], v[50:51]
	v_add_f32_e32 v26, v27, v26
	v_fma_f32 v8, -v58, v60, 1.0
	v_and_b32_e32 v49, 0xffff0000, v37
	v_lshlrev_b32_e32 v48, 16, v37
	v_add_f32_e32 v10, v10, v26
	v_fmac_f32_e32 v60, v8, v60
	v_pk_mul_f32 v[8:9], v[48:49], v[48:49]
	v_add_f32_e32 v10, v11, v10
	v_add_f32_e32 v8, v8, v10
	v_add_f32_e32 v8, v9, v8
	ds_swizzle_b32 v9, v8 offset:swizzle(SWAP,1)
	v_div_scale_f32 v10, vcc, 1.0, v56, 1.0
	v_mul_f32_e32 v11, v10, v60
	v_fma_f32 v26, -v58, v11, v10
	s_waitcnt lgkmcnt(0)
	v_add_f32_e32 v8, v8, v9
	ds_swizzle_b32 v9, v8 offset:swizzle(SWAP,2)
	v_fmac_f32_e32 v11, v26, v60
	v_fma_f32 v10, -v58, v11, v10
	v_div_fmas_f32 v10, v10, v60, v11
	v_div_fixup_f32 v26, v10, v56, 1.0
	s_waitcnt lgkmcnt(0)
	v_add_f32_e32 v27, v8, v9
	ds_swizzle_b32 v34, v27 offset:swizzle(SWAP,4)
	v_pk_mul_f32 v[8:9], v[26:27], v[42:43] op_sel_hi:[0,1]
	v_pk_mul_f32 v[10:11], v[26:27], v[46:47] op_sel_hi:[0,1]
	v_pk_mul_f32 v[8:9], v[4:5], v[8:9]
	v_pk_mul_f32 v[10:11], v[6:7], v[10:11]
	s_waitcnt lgkmcnt(0)
	v_add_f32_e32 v27, v27, v34
	ds_swizzle_b32 v34, v27 offset:swizzle(SWAP,8)
	v_cvt_pk_bf16_f32 v8, v8, v9
	v_cvt_pk_bf16_f32 v9, v10, v11
	v_pk_mul_f32 v[10:11], v[26:27], v[44:45] op_sel_hi:[0,1]
	v_pk_mul_f32 v[10:11], v[0:1], v[10:11]
	s_waitcnt lgkmcnt(0)
	v_add_f32_e32 v27, v27, v34
	v_fmamk_f32 v27, v27, 0x3c000000, v224
	v_mul_f32_e32 v34, 0x4f800000, v27
	v_cmp_gt_f32_e32 vcc, s18, v27
	v_cvt_pk_bf16_f32 v10, v10, v11
	s_nop 0
	v_and_b32_e32 v45, 0xffff0000, v38
	v_cndmask_b32_e32 v34, v27, v34, vcc
	v_sqrt_f32_e32 v35, v34
	v_pk_mul_f32 v[26:27], v[26:27], v[28:29] op_sel_hi:[0,1]
	v_pk_mul_f32 v[26:27], v[2:3], v[26:27]
	v_lshlrev_b32_e32 v44, 16, v38
	v_add_u32_e32 v11, -1, v35
	v_fma_f32 v28, -v11, v35, v34
	v_cmp_ge_f32_e64 s[36:37], 0, v28
	v_add_u32_e32 v28, 1, v35
	v_fma_f32 v29, -v28, v35, v34
	v_cndmask_b32_e64 v11, v35, v11, s[36:37]
	v_cmp_lt_f32_e64 s[36:37], 0, v29
	v_and_b32_e32 v43, 0xffff0000, v39
	v_lshlrev_b32_e32 v42, 16, v39
	v_cndmask_b32_e64 v11, v11, v28, s[36:37]
	v_mul_f32_e32 v28, 0x37800000, v11
	v_cndmask_b32_e32 v11, v11, v28, vcc
	v_cmp_class_f32_e32 vcc, v34, v250
	v_pk_mul_f32 v[38:39], v[44:45], v[44:45]
	v_and_b32_e32 v29, 0xffff0000, v40
	v_cndmask_b32_e32 v46, v11, v34, vcc
	v_div_scale_f32 v47, s[8:9], v46, v46, 1.0
	v_cvt_pk_bf16_f32 v11, v26, v27
	s_mov_b64 s[8:9], 0x140000
	ds_write_b128 v30, v[8:11] offset:16384
	ds_write_b128 v31, v[16:19] offset:16384
	v_lshl_add_u64 v[10:11], v[24:25], 0, s[8:9]
	s_mov_b32 s8, 0x140000
	v_add_co_u32_e32 v34, vcc, s8, v24
	v_rcp_f32_e32 v56, v47
	s_nop 0
	v_addc_co_u32_e32 v35, vcc, 0, v25, vcc
	s_waitcnt vmcnt(4)
	v_mov_b32_e32 v16, v120
	v_mov_b32_e32 v17, v121
	v_mov_b32_e32 v18, v122
	v_mov_b32_e32 v19, v123
	s_nop 0
	v_mov_b32_e32 v34, v124
	v_mov_b32_e32 v35, v125
	v_mov_b32_e32 v36, v126
	v_mov_b32_e32 v37, v127
	v_and_b32_e32 v27, 0xffff0000, v41
	v_lshlrev_b32_e32 v26, 16, v41
	v_lshlrev_b32_e32 v28, 16, v40
	v_pk_mul_f32 v[40:41], v[42:43], v[42:43]
	v_add_f32_e32 v38, v38, v39
	v_add_f32_e32 v38, v40, v38
	v_pk_mul_f32 v[10:11], v[28:29], v[28:29]
	v_add_f32_e32 v38, v41, v38
	v_fma_f32 v8, -v47, v56, 1.0
	v_add_f32_e32 v10, v10, v38
	v_fmac_f32_e32 v56, v8, v56
	v_pk_mul_f32 v[8:9], v[26:27], v[26:27]
	v_add_f32_e32 v10, v11, v10
	v_add_f32_e32 v8, v8, v10
	v_add_f32_e32 v8, v9, v8
	ds_swizzle_b32 v9, v8 offset:swizzle(SWAP,1)
	v_div_scale_f32 v10, vcc, 1.0, v46, 1.0
	v_mul_f32_e32 v11, v10, v56
	v_fma_f32 v38, -v47, v11, v10
	s_waitcnt lgkmcnt(0)
; template <int X> __device__ __forceinline__ float swz_xor(float v) { return __int_as_float(__builtin_amdgcn_ds_swizzle(__float_as_int(v), (X << 10) | 0x1f)); }
; __device__ __forceinline__ unsigned cvtpk(float lo, float hi) { f32x2_t v = {lo, hi}; bf16x2_t b = __builtin_convertvector(v, bf16x2_t); return __builtin_bit_cast(unsigned, b); }
; __device__ __forceinline__ float bf2f(unsigned short h) { return __uint_as_float(((unsigned)h) << 16); }
; __device__ __forceinline__ int v_st(int k, int c) { const int kk = (k & ~0xC) | ((k & 4) << 1) | ((k & 8) >> 1); return ((kk >> 3) * 4 + (c >> 5)) * 512 + ((kk & 7) * 32 + (c & 31)) * 2; }
; __device__ __forceinline__ void mem_unit(const MemArgs& A, int unit, char* lds, int wv) {
;     ...
;         for (int hh = 0; hh < 2; ++hh) { const int key = t * 64 + hh * 32 + sr;
;           const bf16x8 v8 = *reinterpret_cast<const bf16x8*>(&Vh[(size_t)key * MKVC + sc]); const bf16x8 k8 = *reinterpret_cast<const bf16x8*>(&Kh[(size_t)key * MKVC + sc]);
;           float f[8]; float ss = 0.f;
; #pragma unroll
;           for (int i = 0; i < 8; ++i) { f[i] = bf2f((unsigned short)k8[i]); ss += f[i] * f[i]; }
;           ss += swz_xor<1>(ss); ss += swz_xor<2>(ss); ss += swz_xor<4>(ss); ss += swz_xor<8>(ss);
;           const float rn = 1.0f / sqrtf(ss * (1.0f / 128.0f) + EPS);
;           u32x4 w; w.x = cvtpk(f[0] * rn * g0.x, f[1] * rn * g0.y); w.y = cvtpk(f[2] * rn * g0.z, f[3] * rn * g0.w); w.z = cvtpk(f[4] * rn * g1.x, f[5] * rn * g1.y); w.w = cvtpk(f[6] * rn * g1.z, f[7] * rn * g1.w);
;           *(u32x4*)(K_lds + t * SHM_K + KSWZ(hh * 32 + sr, kc)) = w;
;           { const int ks_ = hh * 32 + sr, kp_ = (ks_ & ~0xC) | ((ks_ & 4) << 1) | ((ks_ & 8) >> 1);
;             *(bf16x8*)(V_lds + t * SHM_V + v_st(kp_, sc)) = v8; } } }
	v_add_f32_e32 v8, v8, v9
	ds_swizzle_b32 v9, v8 offset:swizzle(SWAP,2)
	v_fmac_f32_e32 v11, v38, v56
	v_fma_f32 v10, -v47, v11, v10
	v_div_fmas_f32 v10, v10, v56, v11
	v_div_fixup_f32 v38, v10, v46, 1.0
	s_waitcnt lgkmcnt(0)
	v_add_f32_e32 v39, v8, v9
	ds_swizzle_b32 v40, v39 offset:swizzle(SWAP,4)
	v_pk_mul_f32 v[8:9], v[38:39], v[54:55] op_sel_hi:[0,1]
	v_pk_mul_f32 v[10:11], v[38:39], v[52:53] op_sel_hi:[0,1]
	v_pk_mul_f32 v[8:9], v[4:5], v[8:9]
	v_pk_mul_f32 v[10:11], v[6:7], v[10:11]
	s_waitcnt lgkmcnt(0)
	v_add_f32_e32 v39, v39, v40
	ds_swizzle_b32 v40, v39 offset:swizzle(SWAP,8)
	v_cvt_pk_bf16_f32 v8, v8, v9
	v_cvt_pk_bf16_f32 v9, v10, v11
	v_pk_mul_f32 v[10:11], v[38:39], v[50:51] op_sel_hi:[0,1]
	v_pk_mul_f32 v[10:11], v[0:1], v[10:11]
	s_waitcnt lgkmcnt(0)
	v_add_f32_e32 v39, v39, v40
	v_fmamk_f32 v39, v39, 0x3c000000, v224
	v_mul_f32_e32 v40, 0x4f800000, v39
	v_cmp_gt_f32_e32 vcc, s18, v39
	v_cvt_pk_bf16_f32 v10, v10, v11
	s_nop 0
	v_and_b32_e32 v47, 0xffff0000, v37
	v_cndmask_b32_e32 v40, v39, v40, vcc
	v_sqrt_f32_e32 v41, v40
	v_pk_mul_f32 v[38:39], v[38:39], v[48:49] op_sel_hi:[0,1]
	v_pk_mul_f32 v[38:39], v[2:3], v[38:39]
	v_and_b32_e32 v49, 0xffff0000, v35
	v_add_u32_e32 v11, -1, v41
	v_fma_f32 v46, -v11, v41, v40
	v_cmp_ge_f32_e64 s[36:37], 0, v46
	v_add_u32_e32 v46, 1, v41
	v_lshlrev_b32_e32 v48, 16, v35
	v_cndmask_b32_e64 v11, v41, v11, s[36:37]
	v_fma_f32 v41, -v46, v41, v40
	v_cmp_lt_f32_e64 s[36:37], 0, v41
	v_and_b32_e32 v35, 0xffff0000, v34
	v_lshlrev_b32_e32 v34, 16, v34
	v_cndmask_b32_e64 v11, v11, v46, s[36:37]
	v_mul_f32_e32 v41, 0x37800000, v11
	v_cndmask_b32_e32 v11, v11, v41, vcc
	v_cmp_class_f32_e32 vcc, v40, v250
	v_pk_mul_f32 v[52:53], v[34:35], v[34:35]
	v_pk_mul_f32 v[50:51], v[48:49], v[48:49]
	v_cndmask_b32_e32 v54, v11, v40, vcc
	v_div_scale_f32 v55, s[8:9], v54, v54, 1.0
	v_rcp_f32_e32 v56, v55
	v_cvt_pk_bf16_f32 v11, v38, v39
	ds_write_b128 v32, v[8:11] offset:16384
	ds_write_b128 v33, v[12:15] offset:16384
	s_mov_b64 s[8:9], 0x180000
	v_fma_f32 v8, -v55, v56, 1.0
	v_fmac_f32_e32 v56, v8, v56
	v_lshl_add_u64 v[8:9], v[24:25], 0, s[8:9]
	s_mov_b32 s8, 0x180000
	v_add_co_u32_e32 v12, vcc, s8, v24
	v_add_f32_e32 v52, v52, v53
	s_nop 0
	v_addc_co_u32_e32 v13, vcc, 0, v25, vcc
	s_waitcnt vmcnt(2)
	v_mov_b32_e32 v8, v128
	v_mov_b32_e32 v9, v129
	v_mov_b32_e32 v10, v130
	v_mov_b32_e32 v11, v131
	s_nop 0
	v_mov_b32_e32 v38, v132
	v_mov_b32_e32 v39, v133
	v_mov_b32_e32 v40, v134
	v_mov_b32_e32 v41, v135
	v_lshlrev_b32_e32 v46, 16, v37
	v_and_b32_e32 v37, 0xffff0000, v36
	v_lshlrev_b32_e32 v36, 16, v36
	v_add_f32_e32 v50, v50, v52
	v_pk_mul_f32 v[14:15], v[36:37], v[36:37]
	v_add_f32_e32 v50, v51, v50
	v_add_f32_e32 v14, v14, v50
	v_pk_mul_f32 v[12:13], v[46:47], v[46:47]
	v_add_f32_e32 v14, v15, v14
	v_add_f32_e32 v12, v12, v14
	v_add_f32_e32 v12, v13, v12
	ds_swizzle_b32 v13, v12 offset:swizzle(SWAP,1)
	v_div_scale_f32 v57, vcc, 1.0, v54, 1.0
	v_mul_f32_e32 v58, v57, v56
	v_fma_f32 v59, -v55, v58, v57
	s_waitcnt lgkmcnt(0)
	v_add_f32_e32 v15, v12, v13
	ds_swizzle_b32 v51, v15 offset:swizzle(SWAP,2)
	v_fmac_f32_e32 v58, v59, v56
	v_fma_f32 v14, -v55, v58, v57
	v_div_fmas_f32 v14, v14, v56, v58
	v_div_fixup_f32 v50, v14, v54, 1.0
	s_waitcnt lgkmcnt(0)
	v_pk_mul_f32 v[12:13], v[50:51], v[44:45] op_sel_hi:[0,1]
	v_add_f32_e32 v44, v15, v51
	ds_swizzle_b32 v45, v44 offset:swizzle(SWAP,4)
	v_pk_mul_f32 v[14:15], v[50:51], v[42:43] op_sel_hi:[0,1]
	v_pk_mul_f32 v[12:13], v[4:5], v[12:13]
	v_pk_mul_f32 v[14:15], v[6:7], v[14:15]
	v_cvt_pk_bf16_f32 v12, v12, v13
	v_cvt_pk_bf16_f32 v13, v14, v15
	v_pk_mul_f32 v[14:15], v[50:51], v[28:29] op_sel_hi:[0,1]
	s_waitcnt lgkmcnt(0)
	v_add_f32_e32 v28, v44, v45
	ds_swizzle_b32 v29, v28 offset:swizzle(SWAP,8)
	v_pk_mul_f32 v[14:15], v[0:1], v[14:15]
	v_pk_mul_f32 v[26:27], v[50:51], v[26:27] op_sel_hi:[0,1]
	v_cvt_pk_bf16_f32 v14, v14, v15
	v_pk_mul_f32 v[26:27], v[2:3], v[26:27]
	s_waitcnt lgkmcnt(0)
	v_add_f32_e32 v15, v28, v29
	v_fmamk_f32 v15, v15, 0x3c000000, v224
	v_mul_f32_e32 v28, 0x4f800000, v15
	v_cmp_gt_f32_e32 vcc, s18, v15
	s_nop 0
	v_and_b32_e32 v51, 0xffff0000, v38
	v_cndmask_b32_e32 v28, v15, v28, vcc
	v_sqrt_f32_e32 v29, v28
	v_cvt_pk_bf16_f32 v15, v26, v27
	ds_write_b128 v30, v[12:15] offset:32768
	ds_write_b128 v31, v[20:23] offset:32768
	v_lshlrev_b32_e32 v50, 16, v38
	v_add_u32_e32 v12, -1, v29
	v_fma_f32 v13, -v12, v29, v28
	v_cmp_ge_f32_e64 s[36:37], 0, v13
	v_add_u32_e32 v13, 1, v29
	v_fma_f32 v14, -v13, v29, v28
	v_cndmask_b32_e64 v12, v29, v12, s[36:37]
	v_cmp_lt_f32_e64 s[36:37], 0, v14
	v_and_b32_e32 v45, 0xffff0000, v39
	v_lshlrev_b32_e32 v44, 16, v39
	v_cndmask_b32_e64 v12, v12, v13, s[36:37]
	v_mul_f32_e32 v13, 0x37800000, v12
	v_cndmask_b32_e32 v12, v12, v13, vcc
	v_cmp_class_f32_e32 vcc, v28, v250
	v_pk_mul_f32 v[38:39], v[50:51], v[50:51]
	v_and_b32_e32 v29, 0xffff0000, v41
	v_cndmask_b32_e32 v52, v12, v28, vcc
	v_div_scale_f32 v53, s[8:9], v52, v52, 1.0
	s_mov_b64 s[8:9], 0x1c0000
	s_nop 0
	v_lshl_add_u64 v[12:13], v[24:25], 0, s[8:9]
	s_mov_b32 s8, 0x1c0000
	v_add_co_u32_e32 v20, vcc, s8, v24
	v_rcp_f32_e32 v54, v53
	s_nop 0
	v_addc_co_u32_e32 v21, vcc, 0, v25, vcc
	s_waitcnt vmcnt(0)
	v_mov_b32_e32 v12, v136
	v_mov_b32_e32 v13, v137
	v_mov_b32_e32 v14, v138
	v_mov_b32_e32 v15, v139
	s_nop 0
	v_mov_b32_e32 v20, v140
	v_mov_b32_e32 v21, v141
	v_mov_b32_e32 v22, v142
	v_mov_b32_e32 v23, v143
	v_lshlrev_b32_e32 v28, 16, v41
	v_and_b32_e32 v43, 0xffff0000, v40
	v_lshlrev_b32_e32 v42, 16, v40
	v_pk_mul_f32 v[40:41], v[44:45], v[44:45]
	v_add_f32_e32 v38, v38, v39
	v_add_f32_e32 v38, v40, v38
	v_pk_mul_f32 v[26:27], v[42:43], v[42:43]
	v_add_f32_e32 v38, v41, v38
	v_fma_f32 v24, -v53, v54, 1.0
	v_add_f32_e32 v26, v26, v38
	v_fmac_f32_e32 v54, v24, v54
	v_pk_mul_f32 v[24:25], v[28:29], v[28:29]
	v_add_f32_e32 v26, v27, v26
	v_add_f32_e32 v24, v24, v26
	v_add_f32_e32 v24, v25, v24
	ds_swizzle_b32 v25, v24 offset:swizzle(SWAP,1)
	v_div_scale_f32 v26, vcc, 1.0, v52, 1.0
	v_mul_f32_e32 v27, v26, v54
	v_fma_f32 v38, -v53, v27, v26
	s_waitcnt lgkmcnt(0)
; template <int X> __device__ __forceinline__ float swz_xor(float v) { return __int_as_float(__builtin_amdgcn_ds_swizzle(__float_as_int(v), (X << 10) | 0x1f)); }
; __device__ __forceinline__ unsigned cvtpk(float lo, float hi) { f32x2_t v = {lo, hi}; bf16x2_t b = __builtin_convertvector(v, bf16x2_t); return __builtin_bit_cast(unsigned, b); }
; __device__ __forceinline__ float bf2f(unsigned short h) { return __uint_as_float(((unsigned)h) << 16); }
; __device__ __forceinline__ int v_st(int k, int c) { const int kk = (k & ~0xC) | ((k & 4) << 1) | ((k & 8) >> 1); return ((kk >> 3) * 4 + (c >> 5)) * 512 + ((kk & 7) * 32 + (c & 31)) * 2; }
; __device__ __forceinline__ void mem_unit(const MemArgs& A, int unit, char* lds, int wv) {
;     ...
;         for (int hh = 0; hh < 2; ++hh) { const int key = t * 64 + hh * 32 + sr;
;           const bf16x8 v8 = *reinterpret_cast<const bf16x8*>(&Vh[(size_t)key * MKVC + sc]); const bf16x8 k8 = *reinterpret_cast<const bf16x8*>(&Kh[(size_t)key * MKVC + sc]);
;           float f[8]; float ss = 0.f;
; #pragma unroll
;           for (int i = 0; i < 8; ++i) { f[i] = bf2f((unsigned short)k8[i]); ss += f[i] * f[i]; }
;           ss += swz_xor<1>(ss); ss += swz_xor<2>(ss); ss += swz_xor<4>(ss); ss += swz_xor<8>(ss);
;           const float rn = 1.0f / sqrtf(ss * (1.0f / 128.0f) + EPS);
;           u32x4 w; w.x = cvtpk(f[0] * rn * g0.x, f[1] * rn * g0.y); w.y = cvtpk(f[2] * rn * g0.z, f[3] * rn * g0.w); w.z = cvtpk(f[4] * rn * g1.x, f[5] * rn * g1.y); w.w = cvtpk(f[6] * rn * g1.z, f[7] * rn * g1.w);
;           *(u32x4*)(K_lds + t * SHM_K + KSWZ(hh * 32 + sr, kc)) = w;
;           { const int ks_ = hh * 32 + sr, kp_ = (ks_ & ~0xC) | ((ks_ & 4) << 1) | ((ks_ & 8) >> 1);
;             *(bf16x8*)(V_lds + t * SHM_V + v_st(kp_, sc)) = v8; } } }
;     bf16x8 qr[8];
;     const size_t grow0 = (size_t)b * SEQ + qb * 256 + wid * 32;
;     { const bf16* Qw = A.proj + (grow0 + r32) * INC + C_MQ + hm * 128 + hi * 8;
;       bf16x8 raw[8]; float ss = 0.f;
; #pragma unroll
;       for (int d0 = 0; d0 < 8; ++d0) { raw[d0] = *reinterpret_cast<const bf16x8*>(Qw + d0 * 16);
	v_add_f32_e32 v24, v24, v25
	ds_swizzle_b32 v25, v24 offset:swizzle(SWAP,2)
	v_fmac_f32_e32 v27, v38, v54
	v_fma_f32 v26, -v53, v27, v26
	v_div_fmas_f32 v26, v26, v54, v27
	v_div_fixup_f32 v38, v26, v52, 1.0
	s_waitcnt lgkmcnt(0)
	v_add_f32_e32 v39, v24, v25
	ds_swizzle_b32 v40, v39 offset:swizzle(SWAP,4)
	v_pk_mul_f32 v[24:25], v[38:39], v[34:35] op_sel_hi:[0,1]
	v_pk_mul_f32 v[26:27], v[38:39], v[48:49] op_sel_hi:[0,1]
	v_pk_mul_f32 v[24:25], v[4:5], v[24:25]
	v_pk_mul_f32 v[26:27], v[6:7], v[26:27]
	s_waitcnt lgkmcnt(0)
	v_add_f32_e32 v34, v39, v40
	ds_swizzle_b32 v35, v34 offset:swizzle(SWAP,8)
	v_cvt_pk_bf16_f32 v24, v24, v25
	v_cvt_pk_bf16_f32 v25, v26, v27
	v_pk_mul_f32 v[26:27], v[38:39], v[36:37] op_sel_hi:[0,1]
	v_pk_mul_f32 v[26:27], v[0:1], v[26:27]
	s_waitcnt lgkmcnt(0)
	v_add_f32_e32 v34, v34, v35
	v_fmamk_f32 v34, v34, 0x3c000000, v224
	v_mul_f32_e32 v35, 0x4f800000, v34
	v_cmp_gt_f32_e32 vcc, s18, v34
	v_cvt_pk_bf16_f32 v26, v26, v27
	s_nop 0
	v_cndmask_b32_e32 v36, v34, v35, vcc
	v_sqrt_f32_e32 v37, v36
	v_pk_mul_f32 v[34:35], v[38:39], v[46:47] op_sel_hi:[0,1]
	v_pk_mul_f32 v[34:35], v[2:3], v[34:35]
	v_add_u32_e32 v27, -1, v37
	v_fma_f32 v38, -v27, v37, v36
	v_cmp_ge_f32_e64 s[36:37], 0, v38
	v_add_u32_e32 v38, 1, v37
	s_nop 0
	v_cndmask_b32_e64 v27, v37, v27, s[36:37]
	v_fma_f32 v37, -v38, v37, v36
	v_cmp_lt_f32_e64 s[36:37], 0, v37
	s_nop 1
	v_cndmask_b32_e64 v27, v27, v38, s[36:37]
	v_mul_f32_e32 v37, 0x37800000, v27
	v_cndmask_b32_e32 v27, v27, v37, vcc
	v_cmp_class_f32_e32 vcc, v36, v250
	s_nop 1
	v_cndmask_b32_e32 v38, v27, v36, vcc
	v_div_scale_f32 v39, s[8:9], v38, v38, 1.0
	v_rcp_f32_e32 v40, v39
	v_cvt_pk_bf16_f32 v27, v34, v35
	ds_write_b128 v32, v[24:27] offset:32768
	ds_write_b128 v33, v[16:19] offset:32768
	v_div_scale_f32 v41, vcc, 1.0, v38, 1.0
	v_fma_f32 v16, -v39, v40, 1.0
	v_fmac_f32_e32 v40, v16, v40
	v_mul_f32_e32 v46, v41, v40
	v_fma_f32 v16, -v39, v46, v41
	v_fmac_f32_e32 v46, v16, v40
	s_lshl_b64 s[8:9], s[84:85], 13
	s_nop 0
	v_and_b32_e32 v27, 0xffff0000, v21
	v_lshlrev_b32_e32 v26, 16, v21
	v_and_b32_e32 v21, 0xffff0000, v20
	v_lshlrev_b32_e32 v20, 16, v20
	v_pk_mul_f32 v[36:37], v[20:21], v[20:21]
	v_pk_mul_f32 v[34:35], v[26:27], v[26:27]
	v_add_f32_e32 v36, v36, v37
	v_and_b32_e32 v25, 0xffff0000, v23
	v_lshlrev_b32_e32 v24, 16, v23
	v_and_b32_e32 v23, 0xffff0000, v22
	v_lshlrev_b32_e32 v22, 16, v22
	v_add_f32_e32 v34, v34, v36
	v_pk_mul_f32 v[18:19], v[22:23], v[22:23]
	v_add_f32_e32 v34, v35, v34
	v_add_f32_e32 v18, v18, v34
	v_pk_mul_f32 v[16:17], v[24:25], v[24:25]
	v_add_f32_e32 v18, v19, v18
	v_add_f32_e32 v16, v16, v18
	v_add_f32_e32 v16, v17, v16
	ds_swizzle_b32 v17, v16 offset:swizzle(SWAP,1)
	s_or_b32 s3, s8, s3
	s_ashr_i32 s8, s1, 1
	s_andn2_b32 s8, s8, 31
	v_fma_f32 v18, -v39, v46, v41
	s_ashr_i32 s16, s8, 31
	v_div_fmas_f32 v18, v18, v40, v46
	s_add_u32 s8, s3, s8
	v_div_fixup_f32 v34, v18, v38, 1.0
	s_waitcnt lgkmcnt(0)
	v_add_f32_e32 v35, v16, v17
	v_or_b32_e32 v18, s8, v144
	v_mov_b64_e32 v[16:17], s[80:81]
	s_addc_u32 s3, s9, s16
	v_mad_u64_u32 v[16:17], s[16:17], v18, s33, v[16:17]
	v_mov_b32_e32 v18, 0x3800
	v_mad_i32_i24 v17, s3, v18, v17
	v_lshl_add_u64 v[16:17], v[16:17], 0, s[6:7]
	v_lshl_add_u64 v[16:17], v[16:17], 0, v[176:177]
	s_mov_b64 s[6:7], 0x3000
	v_lshl_add_u64 v[36:37], v[16:17], 0, s[6:7]
	v_add_co_u32_e32 v16, vcc, s63, v16
	ds_swizzle_b32 v46, v35 offset:swizzle(SWAP,2)
	s_nop 0
	v_addc_co_u32_e32 v17, vcc, 0, v17, vcc
	global_load_dwordx4 v[80:83], v[16:17], off
	global_load_dwordx4 v[38:41], v[36:37], off offset:224
	v_pk_mul_f32 v[16:17], v[34:35], v[50:51] op_sel_hi:[0,1]
	v_pk_mul_f32 v[18:19], v[34:35], v[44:45] op_sel_hi:[0,1]
	s_waitcnt lgkmcnt(0)
	v_add_f32_e32 v35, v35, v46
	global_load_dwordx4 v[54:57], v[36:37], off offset:160
	global_load_dwordx4 v[46:49], v[36:37], off offset:192
	global_load_dwordx4 v[70:73], v[36:37], off offset:96
	global_load_dwordx4 v[62:65], v[36:37], off offset:128
	global_load_dwordx4 v[84:87], v[36:37], off offset:32
	global_load_dwordx4 v[88:91], v[36:37], off offset:64
	ds_swizzle_b32 v44, v35 offset:swizzle(SWAP,4)
	v_pk_mul_f32 v[16:17], v[4:5], v[16:17]
	v_pk_mul_f32 v[18:19], v[6:7], v[18:19]
	v_cvt_pk_bf16_f32 v16, v16, v17
	v_cvt_pk_bf16_f32 v17, v18, v19
	s_waitcnt lgkmcnt(0)
	v_add_f32_e32 v35, v35, v44
	ds_swizzle_b32 v44, v35 offset:swizzle(SWAP,8)
	v_pk_mul_f32 v[18:19], v[34:35], v[42:43] op_sel_hi:[0,1]
	v_pk_mul_f32 v[18:19], v[0:1], v[18:19]
	v_pk_mul_f32 v[28:29], v[34:35], v[28:29] op_sel_hi:[0,1]
	v_cvt_pk_bf16_f32 v18, v18, v19
	s_waitcnt lgkmcnt(0)
	v_add_f32_e32 v19, v35, v44
	v_fmamk_f32 v19, v19, 0x3c000000, v224
	v_mul_f32_e32 v34, 0x4f800000, v19
	v_cmp_gt_f32_e32 vcc, s18, v19
	v_pk_mul_f32 v[28:29], v[2:3], v[28:29]
	s_mov_b32 s9, 0x3e0293ee
	v_cndmask_b32_e32 v19, v19, v34, vcc
	v_sqrt_f32_e32 v34, v19
	s_cmp_lg_u32 0, -1
	v_add_u32_e32 v35, -1, v34
	v_fma_f32 v42, -v35, v34, v19
	v_cmp_ge_f32_e64 s[36:37], 0, v42
	v_add_u32_e32 v42, 1, v34
	s_waitcnt vmcnt(7)
; __device__ __forceinline__ unsigned cvtpk(float lo, float hi) { f32x2_t v = {lo, hi}; bf16x2_t b = __builtin_convertvector(v, bf16x2_t); return __builtin_bit_cast(unsigned, b); }
; __device__ __forceinline__ float bf2f(unsigned short h) { return __uint_as_float(((unsigned)h) << 16); }
; __device__ __forceinline__ int v_st(int k, int c) { const int kk = (k & ~0xC) | ((k & 4) << 1) | ((k & 8) >> 1); return ((kk >> 3) * 4 + (c >> 5)) * 512 + ((kk & 7) * 32 + (c & 31)) * 2; }
; __device__ __forceinline__ void mem_unit(const MemArgs& A, int unit, char* lds, int wv) {
;     ...
;           u32x4 w; w.x = cvtpk(f[0] * rn * g0.x, f[1] * rn * g0.y); w.y = cvtpk(f[2] * rn * g0.z, f[3] * rn * g0.w); w.z = cvtpk(f[4] * rn * g1.x, f[5] * rn * g1.y); w.w = cvtpk(f[6] * rn * g1.z, f[7] * rn * g1.w);
;           *(u32x4*)(K_lds + t * SHM_K + KSWZ(hh * 32 + sr, kc)) = w;
;           { const int ks_ = hh * 32 + sr, kp_ = (ks_ & ~0xC) | ((ks_ & 4) << 1) | ((ks_ & 8) >> 1);
;             *(bf16x8*)(V_lds + t * SHM_V + v_st(kp_, sc)) = v8; } } }
;     bf16x8 qr[8];
;     const size_t grow0 = (size_t)b * SEQ + qb * 256 + wid * 32;
;     { const bf16* Qw = A.proj + (grow0 + r32) * INC + C_MQ + hm * 128 + hi * 8;
;       bf16x8 raw[8]; float ss = 0.f;
; #pragma unroll
;       for (int d0 = 0; d0 < 8; ++d0) { raw[d0] = *reinterpret_cast<const bf16x8*>(Qw + d0 * 16);
; #pragma unroll
;           for (int i = 0; i < 8; ++i) { const float f = bf2f((unsigned short)raw[d0][i]); ss += f * f; } }
	v_and_b32_e32 v113, 0xffff0000, v80
	v_cndmask_b32_e64 v35, v34, v35, s[36:37]
	v_fma_f32 v34, -v42, v34, v19
	v_cmp_lt_f32_e64 s[36:37], 0, v34
	v_lshlrev_b32_e32 v112, 16, v80
	v_mul_f32_e32 v80, v113, v113
	v_cndmask_b32_e64 v34, v35, v42, s[36:37]
	v_mul_f32_e32 v35, 0x37800000, v34
	v_cndmask_b32_e32 v34, v34, v35, vcc
	v_cmp_class_f32_e32 vcc, v19, v250
	v_and_b32_e32 v129, 0xffff0000, v81
	v_lshlrev_b32_e32 v128, 16, v81
	v_cndmask_b32_e32 v34, v34, v19, vcc
	v_div_scale_f32 v35, s[6:7], v34, v34, 1.0
	v_rcp_f32_e32 v36, v35
	v_pk_fma_f32 v[80:81], v[112:113], v[112:113], v[80:81] op_sel_hi:[1,1,0]
	v_and_b32_e32 v115, 0xffff0000, v82
	v_lshlrev_b32_e32 v114, 16, v82
	v_pk_fma_f32 v[80:81], v[128:129], v[128:129], v[80:81]
	v_mul_f32_e32 v82, v129, v129
	v_pk_add_f32 v[80:81], v[82:83], v[80:81] op_sel_hi:[0,1]
	v_cvt_pk_bf16_f32 v19, v28, v29
	v_pk_fma_f32 v[80:81], v[114:115], v[114:115], v[80:81]
	v_mul_f32_e32 v82, v115, v115
	ds_write_b128 v30, v[16:19] offset:49152
	ds_write_b128 v31, v[8:11] offset:49152
	v_fma_f32 v8, -v35, v36, 1.0
	v_and_b32_e32 v127, 0xffff0000, v83
	v_lshlrev_b32_e32 v126, 16, v83
	v_pk_add_f32 v[80:81], v[82:83], v[80:81] op_sel_hi:[0,1]
	v_fmac_f32_e32 v36, v8, v36
	v_div_scale_f32 v8, vcc, 1.0, v34, 1.0
	v_pk_fma_f32 v[80:81], v[126:127], v[126:127], v[80:81]
	v_mul_f32_e32 v82, v127, v127
	v_mul_f32_e32 v9, v8, v36
	s_waitcnt vmcnt(1)
	v_and_b32_e32 v117, 0xffff0000, v84
	v_lshlrev_b32_e32 v116, 16, v84
	v_pk_add_f32 v[80:81], v[82:83], v[80:81] op_sel_hi:[0,1]
	v_fma_f32 v10, -v35, v9, v8
	v_pk_fma_f32 v[80:81], v[116:117], v[116:117], v[80:81]
	v_mul_f32_e32 v82, v117, v117
	v_fmac_f32_e32 v9, v10, v36
	v_and_b32_e32 v125, 0xffff0000, v85
	v_lshlrev_b32_e32 v124, 16, v85
	v_pk_add_f32 v[80:81], v[82:83], v[80:81] op_sel_hi:[0,1]
	v_fma_f32 v8, -v35, v9, v8
	v_pk_fma_f32 v[80:81], v[124:125], v[124:125], v[80:81]
	v_mul_f32_e32 v82, v125, v125
	v_div_fmas_f32 v8, v8, v36, v9
	v_and_b32_e32 v119, 0xffff0000, v86
	v_lshlrev_b32_e32 v118, 16, v86
	v_pk_add_f32 v[80:81], v[82:83], v[80:81] op_sel_hi:[0,1]
	v_div_fixup_f32 v8, v8, v34, 1.0
	v_pk_fma_f32 v[80:81], v[118:119], v[118:119], v[80:81]
	v_mul_f32_e32 v82, v119, v119
	v_pk_mul_f32 v[10:11], v[8:9], v[20:21] op_sel_hi:[0,1]
	v_and_b32_e32 v123, 0xffff0000, v87
	v_lshlrev_b32_e32 v122, 16, v87
	v_pk_add_f32 v[80:81], v[82:83], v[80:81] op_sel_hi:[0,1]
	v_pk_mul_f32 v[4:5], v[4:5], v[10:11]
	v_pk_mul_f32 v[10:11], v[8:9], v[26:27] op_sel_hi:[0,1]
	v_pk_fma_f32 v[80:81], v[122:123], v[122:123], v[80:81]
	v_mul_f32_e32 v82, v123, v123
	v_pk_mul_f32 v[6:7], v[6:7], v[10:11]
	s_waitcnt vmcnt(0)
	v_and_b32_e32 v121, 0xffff0000, v88
	v_lshlrev_b32_e32 v120, 16, v88
	v_pk_add_f32 v[80:81], v[82:83], v[80:81] op_sel_hi:[0,1]
	v_cvt_pk_bf16_f32 v4, v4, v5
	v_cvt_pk_bf16_f32 v5, v6, v7
	v_pk_mul_f32 v[6:7], v[8:9], v[22:23] op_sel_hi:[0,1]
	v_pk_fma_f32 v[80:81], v[120:121], v[120:121], v[80:81]
	v_mul_f32_e32 v82, v121, v121
	v_pk_mul_f32 v[0:1], v[0:1], v[6:7]
	v_and_b32_e32 v77, 0xffff0000, v89
	v_lshlrev_b32_e32 v76, 16, v89
	v_pk_add_f32 v[80:81], v[82:83], v[80:81] op_sel_hi:[0,1]
	v_cvt_pk_bf16_f32 v6, v0, v1
	v_pk_mul_f32 v[0:1], v[8:9], v[24:25] op_sel_hi:[0,1]
	v_pk_fma_f32 v[80:81], v[76:77], v[76:77], v[80:81]
	v_mul_f32_e32 v82, v77, v77
	v_pk_mul_f32 v[0:1], v[2:3], v[0:1]
	v_and_b32_e32 v75, 0xffff0000, v90
	v_lshlrev_b32_e32 v74, 16, v90
	v_pk_add_f32 v[80:81], v[82:83], v[80:81] op_sel_hi:[0,1]
	v_cvt_pk_bf16_f32 v7, v0, v1
	v_pk_fma_f32 v[80:81], v[74:75], v[74:75], v[80:81]
	v_mul_f32_e32 v82, v75, v75
	ds_write_b128 v32, v[4:7] offset:49152
	ds_write_b128 v33, v[12:15] offset:49152
	v_and_b32_e32 v33, 0xffff0000, v41
	v_lshlrev_b32_e32 v32, 16, v41
	v_and_b32_e32 v35, 0xffff0000, v40
	v_lshlrev_b32_e32 v34, 16, v40
	v_and_b32_e32 v41, 0xffff0000, v49
	v_lshlrev_b32_e32 v40, 16, v49
	v_and_b32_e32 v43, 0xffff0000, v48
	v_lshlrev_b32_e32 v42, 16, v48
	v_and_b32_e32 v49, 0xffff0000, v57
	v_lshlrev_b32_e32 v48, 16, v57
	v_and_b32_e32 v51, 0xffff0000, v56
	v_lshlrev_b32_e32 v50, 16, v56
	v_and_b32_e32 v57, 0xffff0000, v65
	v_lshlrev_b32_e32 v56, 16, v65
	v_and_b32_e32 v59, 0xffff0000, v64
	v_lshlrev_b32_e32 v58, 16, v64
	v_and_b32_e32 v65, 0xffff0000, v73
	v_lshlrev_b32_e32 v64, 16, v73
	v_and_b32_e32 v67, 0xffff0000, v72
	v_lshlrev_b32_e32 v66, 16, v72
	v_and_b32_e32 v73, 0xffff0000, v91
	v_lshlrev_b32_e32 v72, 16, v91
	v_pk_add_f32 v[80:81], v[82:83], v[80:81] op_sel_hi:[0,1]
	v_pk_fma_f32 v[80:81], v[72:73], v[72:73], v[80:81]
	v_mul_f32_e32 v82, v73, v73
	v_and_b32_e32 v69, 0xffff0000, v71
	v_lshlrev_b32_e32 v68, 16, v71
	v_and_b32_e32 v71, 0xffff0000, v70
	v_lshlrev_b32_e32 v70, 16, v70
	v_pk_add_f32 v[80:81], v[82:83], v[80:81] op_sel_hi:[0,1]
	v_pk_fma_f32 v[80:81], v[70:71], v[70:71], v[80:81]
	v_mul_f32_e32 v82, v71, v71
	v_pk_add_f32 v[80:81], v[82:83], v[80:81] op_sel_hi:[0,1]
	v_pk_fma_f32 v[80:81], v[68:69], v[68:69], v[80:81]
	v_mul_f32_e32 v82, v69, v69
	v_pk_add_f32 v[80:81], v[82:83], v[80:81] op_sel_hi:[0,1]
	v_pk_fma_f32 v[80:81], v[66:67], v[66:67], v[80:81]
	v_mul_f32_e32 v82, v67, v67
	v_pk_add_f32 v[80:81], v[82:83], v[80:81] op_sel_hi:[0,1]
	v_pk_fma_f32 v[80:81], v[64:65], v[64:65], v[80:81]
	v_mul_f32_e32 v82, v65, v65
	v_and_b32_e32 v61, 0xffff0000, v63
	v_lshlrev_b32_e32 v60, 16, v63
	v_and_b32_e32 v63, 0xffff0000, v62
	v_lshlrev_b32_e32 v62, 16, v62
	v_pk_add_f32 v[80:81], v[82:83], v[80:81] op_sel_hi:[0,1]
	v_pk_fma_f32 v[80:81], v[62:63], v[62:63], v[80:81]
	v_mul_f32_e32 v82, v63, v63
	v_pk_add_f32 v[80:81], v[82:83], v[80:81] op_sel_hi:[0,1]
	v_pk_fma_f32 v[80:81], v[60:61], v[60:61], v[80:81]
; __device__ __forceinline__ float bf2f(unsigned short h) { return __uint_as_float(((unsigned)h) << 16); }
; __device__ __forceinline__ void mem_unit(const MemArgs& A, int unit, char* lds, int wv) {
;     ...
;     { const bf16* Qw = A.proj + (grow0 + r32) * INC + C_MQ + hm * 128 + hi * 8;
;       bf16x8 raw[8]; float ss = 0.f;
; #pragma unroll
;       for (int d0 = 0; d0 < 8; ++d0) { raw[d0] = *reinterpret_cast<const bf16x8*>(Qw + d0 * 16);
; #pragma unroll
;           for (int i = 0; i < 8; ++i) { const float f = bf2f((unsigned short)raw[d0][i]); ss += f * f; } }
;       { auto rr = __builtin_amdgcn_permlane32_swap(__float_as_uint(ss), __float_as_uint(ss), false, false); ss = __uint_as_float(rr[0]) + __uint_as_float(rr[1]); }
;       const float rn = QSCALE_M / sqrtf(ss * (1.0f / 128.0f) + EPS);
	v_mul_f32_e32 v82, v61, v61
	v_pk_add_f32 v[80:81], v[82:83], v[80:81] op_sel_hi:[0,1]
	v_pk_fma_f32 v[80:81], v[58:59], v[58:59], v[80:81]
	v_mul_f32_e32 v82, v59, v59
	v_pk_add_f32 v[80:81], v[82:83], v[80:81] op_sel_hi:[0,1]
	v_pk_fma_f32 v[80:81], v[56:57], v[56:57], v[80:81]
	v_mul_f32_e32 v82, v57, v57
	v_and_b32_e32 v53, 0xffff0000, v55
	v_lshlrev_b32_e32 v52, 16, v55
	v_and_b32_e32 v55, 0xffff0000, v54
	v_lshlrev_b32_e32 v54, 16, v54
	v_pk_add_f32 v[80:81], v[82:83], v[80:81] op_sel_hi:[0,1]
	v_pk_fma_f32 v[80:81], v[54:55], v[54:55], v[80:81]
	v_mul_f32_e32 v82, v55, v55
	global_load_dwordx4 v[24:27], v108, s[40:41] offset:16
	global_load_dwordx4 v[28:31], v108, s[40:41]
	global_load_dwordx4 v[16:19], v108, s[40:41] offset:80
	global_load_dwordx4 v[20:23], v108, s[40:41] offset:64
	global_load_dwordx4 v[8:11], v108, s[40:41] offset:144
	global_load_dwordx4 v[12:15], v108, s[40:41] offset:128
	global_load_dwordx4 v[0:3], v108, s[40:41] offset:208
	global_load_dwordx4 v[4:7], v108, s[40:41] offset:192
	v_pk_add_f32 v[80:81], v[82:83], v[80:81] op_sel_hi:[0,1]
	v_pk_fma_f32 v[80:81], v[52:53], v[52:53], v[80:81]
	v_mul_f32_e32 v82, v53, v53
	v_pk_add_f32 v[80:81], v[82:83], v[80:81] op_sel_hi:[0,1]
	v_pk_fma_f32 v[80:81], v[50:51], v[50:51], v[80:81]
	v_mul_f32_e32 v82, v51, v51
	v_pk_add_f32 v[80:81], v[82:83], v[80:81] op_sel_hi:[0,1]
	v_pk_fma_f32 v[80:81], v[48:49], v[48:49], v[80:81]
	v_mul_f32_e32 v82, v49, v49
	v_and_b32_e32 v45, 0xffff0000, v47
	v_lshlrev_b32_e32 v44, 16, v47
	v_and_b32_e32 v47, 0xffff0000, v46
	v_lshlrev_b32_e32 v46, 16, v46
	v_pk_add_f32 v[80:81], v[82:83], v[80:81] op_sel_hi:[0,1]
	v_pk_fma_f32 v[80:81], v[46:47], v[46:47], v[80:81]
	v_mul_f32_e32 v82, v47, v47
	v_pk_add_f32 v[80:81], v[82:83], v[80:81] op_sel_hi:[0,1]
	v_pk_fma_f32 v[80:81], v[44:45], v[44:45], v[80:81]
	v_mul_f32_e32 v82, v45, v45
	v_pk_add_f32 v[80:81], v[82:83], v[80:81] op_sel_hi:[0,1]
	v_pk_fma_f32 v[80:81], v[42:43], v[42:43], v[80:81]
	v_mul_f32_e32 v82, v43, v43
	v_pk_add_f32 v[80:81], v[82:83], v[80:81] op_sel_hi:[0,1]
	v_pk_fma_f32 v[80:81], v[40:41], v[40:41], v[80:81]
	v_mul_f32_e32 v82, v41, v41
	v_and_b32_e32 v37, 0xffff0000, v39
	v_lshlrev_b32_e32 v36, 16, v39
	v_and_b32_e32 v39, 0xffff0000, v38
	v_lshlrev_b32_e32 v38, 16, v38
	v_pk_add_f32 v[80:81], v[82:83], v[80:81] op_sel_hi:[0,1]
	v_pk_fma_f32 v[80:81], v[38:39], v[38:39], v[80:81]
	v_mul_f32_e32 v82, v39, v39
	v_pk_add_f32 v[80:81], v[82:83], v[80:81] op_sel_hi:[0,1]
	v_pk_fma_f32 v[80:81], v[36:37], v[36:37], v[80:81]
	v_mul_f32_e32 v82, v37, v37
	v_pk_add_f32 v[80:81], v[82:83], v[80:81] op_sel_hi:[0,1]
	v_pk_fma_f32 v[80:81], v[34:35], v[34:35], v[80:81]
	v_mul_f32_e32 v82, v35, v35
	v_pk_add_f32 v[80:81], v[82:83], v[80:81] op_sel_hi:[0,1]
	v_pk_fma_f32 v[80:81], v[32:33], v[32:33], v[80:81]
	v_mul_f32_e32 v82, v33, v33
	v_pk_add_f32 v[80:81], v[82:83], v[80:81] op_sel_hi:[0,1]
	v_mov_b32_e32 v81, v80
	s_nop 1
	v_permlane32_swap_b32_e32 v80, v81
	v_add_f32_e32 v80, v80, v81
	v_fmamk_f32 v80, v80, 0x3c000000, v224
	v_mul_f32_e32 v81, 0x4f800000, v80
	v_cmp_gt_f32_e32 vcc, s18, v80
	s_nop 1
	v_cndmask_b32_e32 v96, v80, v81, vcc
	global_load_dwordx4 v[80:83], v108, s[40:41] offset:272
	global_load_dwordx4 v[84:87], v108, s[40:41] offset:256
	global_load_dwordx4 v[88:91], v108, s[40:41] offset:336
	global_load_dwordx4 v[92:95], v108, s[40:41] offset:320
	v_sqrt_f32_e32 v97, v96
	s_nop 0
	v_add_u32_e32 v98, -1, v97
	v_fma_f32 v99, -v98, v97, v96
	v_cmp_ge_f32_e64 s[36:37], 0, v99
	v_add_u32_e32 v99, 1, v97
	s_nop 0
	v_cndmask_b32_e64 v98, v97, v98, s[36:37]
	v_fma_f32 v97, -v99, v97, v96
	v_cmp_lt_f32_e64 s[36:37], 0, v97
	s_nop 1
	v_cndmask_b32_e64 v97, v98, v99, s[36:37]
	v_mul_f32_e32 v98, 0x37800000, v97
	v_cndmask_b32_e32 v97, v97, v98, vcc
	v_cmp_class_f32_e32 vcc, v96, v250
	s_nop 1
	v_cndmask_b32_e32 v130, v97, v96, vcc
	global_load_dwordx4 v[96:99], v108, s[40:41] offset:400
	global_load_dwordx4 v[100:103], v108, s[40:41] offset:384
	global_load_dwordx4 v[104:107], v108, s[40:41] offset:464
	s_nop 0
	global_load_dwordx4 v[108:111], v108, s[40:41] offset:448
	v_div_scale_f32 v131, s[6:7], v130, v130, s9
	v_rcp_f32_e32 v132, v131
	s_cselect_b32 s6, 0, 0
	s_waitcnt lgkmcnt(0)
	s_barrier
; __device__ __forceinline__ unsigned cvtpk(float lo, float hi) { f32x2_t v = {lo, hi}; bf16x2_t b = __builtin_convertvector(v, bf16x2_t); return __builtin_bit_cast(unsigned, b); }
; __device__ __forceinline__ float bf2f(unsigned short h) { return __uint_as_float(((unsigned)h) << 16); }
; __device__ __forceinline__ void mem_unit(const MemArgs& A, int unit, char* lds, int wv) {
;     ...
;       const float rn = QSCALE_M / sqrtf(ss * (1.0f / 128.0f) + EPS);
; #pragma unroll
;       for (int d0 = 0; d0 < 8; ++d0) { const f32x4 g0 = *(const f32x4*)(A.gmq + d0 * 16 + hi * 8), g1 = *(const f32x4*)(A.gmq + d0 * 16 + hi * 8 + 4);
;           u32x4 w; w.x = cvtpk(bf2f((unsigned short)raw[d0][0]) * rn * g0.x, bf2f((unsigned short)raw[d0][1]) * rn * g0.y); w.y = cvtpk(bf2f((unsigned short)raw[d0][2]) * rn * g0.z, bf2f((unsigned short)raw[d0][3]) * rn * g0.w);
;           w.z = cvtpk(bf2f((unsigned short)raw[d0][4]) * rn * g1.x, bf2f((unsigned short)raw[d0][5]) * rn * g1.y); w.w = cvtpk(bf2f((unsigned short)raw[d0][6]) * rn * g1.z, bf2f((unsigned short)raw[d0][7]) * rn * g1.w);
;           qr[d0] = *reinterpret_cast<bf16x8*>(&w); } }
	v_fma_f32 v133, -v131, v132, 1.0
	v_fmac_f32_e32 v132, v133, v132
	v_div_scale_f32 v133, vcc, s9, v130, s9
	v_mul_f32_e32 v134, v133, v132
	v_fma_f32 v135, -v131, v134, v133
	v_fmac_f32_e32 v134, v135, v132
	v_fma_f32 v131, -v131, v134, v133
	v_div_fmas_f32 v131, v131, v132, v134
	v_div_fixup_f32 v148, v131, v130, s9
	v_pk_mul_f32 v[112:113], v[148:149], v[112:113] op_sel_hi:[0,1]
	s_waitcnt vmcnt(14)
	v_pk_mul_f32 v[28:29], v[28:29], v[112:113]
	s_nop 0
	v_cvt_pk_bf16_f32 v112, v28, v29
	v_pk_mul_f32 v[28:29], v[148:149], v[128:129] op_sel_hi:[0,1]
	v_pk_mul_f32 v[28:29], v[30:31], v[28:29]
	s_nop 0
	v_cvt_pk_bf16_f32 v113, v28, v29
	v_pk_mul_f32 v[28:29], v[148:149], v[114:115] op_sel_hi:[0,1]
	v_pk_mul_f32 v[24:25], v[24:25], v[28:29]
	s_nop 0
	v_cvt_pk_bf16_f32 v114, v24, v25
	v_pk_mul_f32 v[24:25], v[148:149], v[126:127] op_sel_hi:[0,1]
	v_pk_mul_f32 v[24:25], v[26:27], v[24:25]
	s_nop 0
	v_cvt_pk_bf16_f32 v115, v24, v25
	v_pk_mul_f32 v[24:25], v[148:149], v[116:117] op_sel_hi:[0,1]
	s_waitcnt vmcnt(12)
	v_pk_mul_f32 v[20:21], v[20:21], v[24:25]
	s_nop 0
	v_cvt_pk_bf16_f32 v116, v20, v21
	v_pk_mul_f32 v[20:21], v[148:149], v[124:125] op_sel_hi:[0,1]
	v_pk_mul_f32 v[20:21], v[22:23], v[20:21]
	s_nop 0
	v_cvt_pk_bf16_f32 v117, v20, v21
	v_pk_mul_f32 v[20:21], v[148:149], v[118:119] op_sel_hi:[0,1]
	v_pk_mul_f32 v[16:17], v[16:17], v[20:21]
	s_nop 0
	v_cvt_pk_bf16_f32 v118, v16, v17
	v_pk_mul_f32 v[16:17], v[148:149], v[122:123] op_sel_hi:[0,1]
	v_pk_mul_f32 v[16:17], v[18:19], v[16:17]
	s_nop 0
	v_cvt_pk_bf16_f32 v119, v16, v17
	v_pk_mul_f32 v[16:17], v[148:149], v[120:121] op_sel_hi:[0,1]
	s_waitcnt vmcnt(10)
	v_pk_mul_f32 v[12:13], v[12:13], v[16:17]
	v_mov_b32_e32 v16, 0
	v_cvt_pk_bf16_f32 v120, v12, v13
	v_pk_mul_f32 v[12:13], v[148:149], v[76:77] op_sel_hi:[0,1]
	v_pk_mul_f32 v[12:13], v[14:15], v[12:13]
	s_nop 0
	v_cvt_pk_bf16_f32 v121, v12, v13
	v_pk_mul_f32 v[12:13], v[148:149], v[74:75] op_sel_hi:[0,1]
	v_pk_mul_f32 v[8:9], v[8:9], v[12:13]
	v_or_b32_e32 v12, 0xe0, v176
	v_cvt_pk_bf16_f32 v122, v8, v9
	v_pk_mul_f32 v[8:9], v[148:149], v[72:73] op_sel_hi:[0,1]
	v_pk_mul_f32 v[8:9], v[10:11], v[8:9]
	v_or_b32_e32 v11, 0xc0, v176
	v_cvt_pk_bf16_f32 v123, v8, v9
	v_pk_mul_f32 v[8:9], v[148:149], v[70:71] op_sel_hi:[0,1]
	s_waitcnt vmcnt(8)
	v_pk_mul_f32 v[4:5], v[4:5], v[8:9]
	v_or_b32_e32 v10, 0xa0, v176
	v_cvt_pk_bf16_f32 v124, v4, v5
	v_pk_mul_f32 v[4:5], v[148:149], v[68:69] op_sel_hi:[0,1]
	v_pk_mul_f32 v[4:5], v[6:7], v[4:5]
	v_or_b32_e32 v9, 0x80, v176
	v_cvt_pk_bf16_f32 v125, v4, v5
	v_pk_mul_f32 v[4:5], v[148:149], v[66:67] op_sel_hi:[0,1]
	v_pk_mul_f32 v[0:1], v[4:5], v[0:1]
	v_lshlrev_b32_e32 v4, 1, v78
	v_cvt_pk_bf16_f32 v126, v0, v1
	v_pk_mul_f32 v[0:1], v[148:149], v[64:65] op_sel_hi:[0,1]
	v_pk_mul_f32 v[0:1], v[0:1], v[2:3]
	v_lshlrev_b32_e32 v2, 4, v78
	v_cvt_pk_bf16_f32 v127, v0, v1
	v_pk_mul_f32 v[0:1], v[148:149], v[62:63] op_sel_hi:[0,1]
	s_waitcnt vmcnt(6)
	v_pk_mul_f32 v[0:1], v[0:1], v[84:85]
	v_and_b32_e32 v3, 0xc0, v2
	v_cvt_pk_bf16_f32 v128, v0, v1
	v_pk_mul_f32 v[0:1], v[148:149], v[60:61] op_sel_hi:[0,1]
	v_pk_mul_f32 v[0:1], v[0:1], v[86:87]
	v_and_b32_e32 v4, 32, v4
	v_cvt_pk_bf16_f32 v129, v0, v1
	v_pk_mul_f32 v[0:1], v[148:149], v[58:59] op_sel_hi:[0,1]
	v_pk_mul_f32 v[0:1], v[0:1], v[80:81]
	v_lshlrev_b32_e32 v5, 8, v144
	v_cvt_pk_bf16_f32 v130, v0, v1
	v_pk_mul_f32 v[0:1], v[148:149], v[56:57] op_sel_hi:[0,1]
	v_pk_mul_f32 v[0:1], v[0:1], v[82:83]
	v_and_b32_e32 v2, 0xf0, v2
	v_cvt_pk_bf16_f32 v131, v0, v1
	v_pk_mul_f32 v[0:1], v[148:149], v[54:55] op_sel_hi:[0,1]
	s_waitcnt vmcnt(4)
	v_pk_mul_f32 v[0:1], v[0:1], v[92:93]
	v_or_b32_e32 v8, 0x60, v176
	v_cvt_pk_bf16_f32 v132, v0, v1
	v_pk_mul_f32 v[0:1], v[148:149], v[52:53] op_sel_hi:[0,1]
	v_pk_mul_f32 v[0:1], v[0:1], v[94:95]
	v_or_b32_e32 v7, 64, v176
	v_cvt_pk_bf16_f32 v133, v0, v1
	v_pk_mul_f32 v[0:1], v[148:149], v[50:51] op_sel_hi:[0,1]
	v_pk_mul_f32 v[0:1], v[0:1], v[88:89]
	v_or_b32_e32 v6, 32, v176
	v_cvt_pk_bf16_f32 v134, v0, v1
	v_pk_mul_f32 v[0:1], v[148:149], v[48:49] op_sel_hi:[0,1]
	v_pk_mul_f32 v[0:1], v[0:1], v[90:91]
	v_xor_b32_e32 v64, 0x80000000, v79
	v_cvt_pk_bf16_f32 v135, v0, v1
	v_pk_mul_f32 v[0:1], v[148:149], v[46:47] op_sel_hi:[0,1]
	s_waitcnt vmcnt(2)
; __device__ __forceinline__ unsigned cvtpk(float lo, float hi) { f32x2_t v = {lo, hi}; bf16x2_t b = __builtin_convertvector(v, bf16x2_t); return __builtin_bit_cast(unsigned, b); }
; __device__ __forceinline__ float bf2f(unsigned short h) { return __uint_as_float(((unsigned)h) << 16); }
; __device__ __forceinline__ int v_rd_base(int lane) { return ((lane & 3) << 3) | (((lane >> 2) & 3) << 6) | (((lane >> 4) & 1) << 5) | (((lane >> 5) & 1) << 8); }
; __device__ __forceinline__ void mem_unit(const MemArgs& A, int unit, char* lds, int wv) {
;     ...
;           u32x4 w; w.x = cvtpk(bf2f((unsigned short)raw[d0][0]) * rn * g0.x, bf2f((unsigned short)raw[d0][1]) * rn * g0.y); w.y = cvtpk(bf2f((unsigned short)raw[d0][2]) * rn * g0.z, bf2f((unsigned short)raw[d0][3]) * rn * g0.w);
;           w.z = cvtpk(bf2f((unsigned short)raw[d0][4]) * rn * g1.x, bf2f((unsigned short)raw[d0][5]) * rn * g1.y); w.w = cvtpk(bf2f((unsigned short)raw[d0][6]) * rn * g1.z, bf2f((unsigned short)raw[d0][7]) * rn * g1.w);
;           qr[d0] = *reinterpret_cast<bf16x8*>(&w); } }
;     __syncthreads();
;     float l_reg = 0; f32x16 o[4] = {};
;     const int vb0 = (int)(uintptr_t)V_lds + v_rd_base(lane);
; #pragma unroll 1
;     for (int t = 0; t < 4; ++t) {
;         f32x16 p0, p1; bf16x8 pa0, pa1, pa2, pa3;
; #pragma unroll
;         for (int r = 0; r < 16; ++r) { p0[r] = nM2; p1[r] = nM2; }
;         qkt<8>(p0, p1, K_lds + t * SHM_K, qr, r32, hi, 0);
	v_pk_mul_f32 v[0:1], v[0:1], v[100:101]
	v_mov_b32_e32 v65, v64
	v_cvt_pk_bf16_f32 v136, v0, v1
	v_pk_mul_f32 v[0:1], v[148:149], v[44:45] op_sel_hi:[0,1]
	v_pk_mul_f32 v[0:1], v[0:1], v[102:103]
	v_mov_b32_e32 v66, v64
	v_cvt_pk_bf16_f32 v137, v0, v1
	v_pk_mul_f32 v[0:1], v[148:149], v[42:43] op_sel_hi:[0,1]
	v_pk_mul_f32 v[0:1], v[0:1], v[96:97]
	v_mov_b32_e32 v67, v64
	v_cvt_pk_bf16_f32 v138, v0, v1
	v_pk_mul_f32 v[0:1], v[148:149], v[40:41] op_sel_hi:[0,1]
	v_pk_mul_f32 v[0:1], v[0:1], v[98:99]
	v_mov_b32_e32 v68, v64
	v_cvt_pk_bf16_f32 v139, v0, v1
	v_pk_mul_f32 v[0:1], v[148:149], v[38:39] op_sel_hi:[0,1]
	s_waitcnt vmcnt(0)
	v_pk_mul_f32 v[0:1], v[0:1], v[108:109]
	v_mov_b32_e32 v69, v64
	v_cvt_pk_bf16_f32 v140, v0, v1
	v_pk_mul_f32 v[0:1], v[148:149], v[36:37] op_sel_hi:[0,1]
	v_pk_mul_f32 v[0:1], v[0:1], v[110:111]
	v_mov_b32_e32 v70, v64
	v_cvt_pk_bf16_f32 v141, v0, v1
	v_pk_mul_f32 v[0:1], v[148:149], v[34:35] op_sel_hi:[0,1]
	v_pk_mul_f32 v[0:1], v[0:1], v[104:105]
	v_mov_b32_e32 v71, v64
	v_cvt_pk_bf16_f32 v142, v0, v1
	v_pk_mul_f32 v[0:1], v[148:149], v[32:33] op_sel_hi:[0,1]
	v_pk_mul_f32 v[0:1], v[0:1], v[106:107]
	v_mov_b32_e32 v148, 0
	v_cvt_pk_bf16_f32 v143, v0, v1
	v_lshlrev_b32_e32 v0, 3, v145
	v_and_b32_e32 v1, 24, v0
	v_and_b32_e32 v0, 0x100, v0
	v_add3_u32 v0, v0, s6, v3
	v_add3_u32 v147, v0, v4, v1
	v_bitop3_b32 v0, v12, v5, v2 bitop3:0xde
	v_add_u32_e32 v149, 0, v0
	v_bitop3_b32 v0, v11, v5, v2 bitop3:0xde
	v_add_u32_e32 v150, 0, v0
	v_bitop3_b32 v0, v10, v5, v2 bitop3:0xde
	v_add_u32_e32 v151, 0, v0
	v_bitop3_b32 v0, v9, v5, v2 bitop3:0xde
	v_add_u32_e32 v152, 0, v0
	v_bitop3_b32 v0, v8, v5, v2 bitop3:0xde
	v_add_u32_e32 v153, 0, v0
	v_bitop3_b32 v0, v7, v5, v2 bitop3:0xde
	v_add_u32_e32 v154, 0, v0
	v_bitop3_b32 v0, v6, v5, v2 bitop3:0xde
	v_add_u32_e32 v155, 0, v0
	v_bitop3_b32 v0, v176, v5, v2 bitop3:0xde
	v_mov_b32_e32 v72, v64
	v_mov_b32_e32 v73, v64
	v_mov_b32_e32 v74, v64
	v_mov_b32_e32 v75, v64
	v_mov_b32_e32 v76, v64
	v_mov_b32_e32 v77, v64
	v_mov_b32_e32 v78, v64
	v_mov_b32_e32 v79, v64
	v_add_u32_e32 v156, 0, v0
	v_mov_b32_e32 v0, 0
	v_mov_b32_e32 v1, v148
	v_mov_b32_e32 v2, v148
	v_mov_b32_e32 v3, v148
	v_mov_b32_e32 v4, v148
	v_mov_b32_e32 v5, v148
	v_mov_b32_e32 v6, v148
	v_mov_b32_e32 v7, v148
	v_mov_b32_e32 v8, v148
	v_mov_b32_e32 v9, v148
	v_mov_b32_e32 v10, v148
	v_mov_b32_e32 v11, v148
	v_mov_b32_e32 v12, v148
	v_mov_b32_e32 v13, v148
	v_mov_b32_e32 v14, v148
	v_mov_b32_e32 v15, v148
	v_mov_b32_e32 v17, v148
	v_mov_b32_e32 v18, v148
	v_mov_b32_e32 v19, v148
	v_mov_b32_e32 v20, v148
	v_mov_b32_e32 v21, v148
	v_mov_b32_e32 v22, v148
	v_mov_b32_e32 v23, v148
	v_mov_b32_e32 v24, v148
	v_mov_b32_e32 v25, v148
	v_mov_b32_e32 v26, v148
	v_mov_b32_e32 v27, v148
	v_mov_b32_e32 v28, v148
	v_mov_b32_e32 v29, v148
	v_mov_b32_e32 v30, v148
	v_mov_b32_e32 v31, v148
	v_mov_b32_e32 v32, 0
	v_mov_b32_e32 v33, v148
	v_mov_b32_e32 v34, v148
	v_mov_b32_e32 v35, v148
	v_mov_b32_e32 v36, v148
	v_mov_b32_e32 v37, v148
	v_mov_b32_e32 v38, v148
	v_mov_b32_e32 v39, v148
	v_mov_b32_e32 v40, v148
	v_mov_b32_e32 v41, v148
	v_mov_b32_e32 v42, v148
	v_mov_b32_e32 v43, v148
	v_mov_b32_e32 v44, v148
	v_mov_b32_e32 v45, v148
	v_mov_b32_e32 v46, v148
	v_mov_b32_e32 v47, v148
	v_mov_b32_e32 v48, 0
	v_mov_b32_e32 v49, v148
	v_mov_b32_e32 v50, v148
	v_mov_b32_e32 v51, v148
	v_mov_b32_e32 v52, v148
	v_mov_b32_e32 v53, v148
	v_mov_b32_e32 v54, v148
	v_mov_b32_e32 v55, v148
	v_mov_b32_e32 v56, v148
	v_mov_b32_e32 v57, v148
	v_mov_b32_e32 v58, v148
	v_mov_b32_e32 v59, v148
	v_mov_b32_e32 v60, v148
	v_mov_b32_e32 v61, v148
	v_mov_b32_e32 v62, v148
	v_mov_b32_e32 v63, v148
	.p2alignl 6, 3212836864

; __device__ __forceinline__ int opaque_tid(int wv) { int lane_; asm volatile("v_mbcnt_lo_u32_b32 %0, -1, 0\n\tv_mbcnt_hi_u32_b32 %0, -1, %0" : "=v"(lane_)); return wv * 64 + lane_; }
; __device__ __forceinline__ int v_rd_base(int lane) { return ((lane & 3) << 3) | (((lane >> 2) & 3) << 6) | (((lane >> 4) & 1) << 5) | (((lane >> 5) & 1) << 8); }
; #define ENDI() do { asm volatile("s_waitcnt vmcnt(0)" ::: "memory"); __syncthreads(); } while (0)
; #define BIAS(P0, P1, t) bias_init(P0, P1, (float)(iposk - (t) * KVBLK), nslope2, nM2, relw + (t) * KVBLK)
; __device__ __forceinline__ void diff_unit(const DiffArgs& A, int b, int h, int qb, char* lds, int wv) {
;     ...
;     float l_reg = 0; f32x16 o[4] = {}; bf16x8 qr[4];
;     { const char* Qw = Pb + (size_t)(qb * 128 + wq * 32) * (INC * 2) + (C_DQ + c * 64) * 2; const unsigned qoff = (unsigned)((r32 * INC + hi * 8) * 2);
; #pragma unroll
;       for (int d0 = 0; d0 < 4; ++d0) qr[d0] = *reinterpret_cast<const bf16x8*>(Qw + qoff + d0 * 32); }
;     const int colB0 = c * 128;
;     const int krow = wid * 4 + (lane >> 4), kcc = (lane & 15) ^ (krow & 15);
;     const unsigned koff = (unsigned)((krow * INC + kcc * 8) * 2);
;     const int vkey = (wid >> 2) * 16 + (((wid >> 1) & 1) << 3) + (((lane >> 4) & 1) << 2) + ((lane >> 2) & 3)  , vcol = ((wid & 1) * 2 + (lane >> 5)) * 32 + (lane & 3) * 8;
;     const unsigned voff = (unsigned)((vkey * INC + vcol) * 2 + (C_DV - C_DK) * 2);
;     const int vb0 = (int)(uintptr_t)V_lds + v_rd_base(lane);
;     const char* Pk = Pb + (size_t)(t_lo * KVBLK) * (INC * 2) + C_DK * 2; int iposk = ipos - t_lo * KVBLK - 4 * hi; asm volatile("" : "+v"(iposk));     const int relw = t_lo * KVBLK - (qb * 128 + wq * 32);
;     typedef __attribute__((address_space(3))) unsigned lds_u32;
;     __attribute__((address_space(3))) unsigned char* ldsA = (__attribute__((address_space(3))) unsigned char*)lds + wid * 1024;
;     ...
;     f32x16 pA0, pA1, pB0, pB1; bf16x8 pa0, pa1, pa2, pa3; const int NT = nt;
;     STAGE(0); ENDI();
;     STAGE(1);
;     BIAS(pA0, pA1, 0); qkt<4>(pA0, pA1, K_lds, qr, r32, hi, colB0);
;     ...
;     if (c == 0) {
;     ...
;         const int lp_ = opaque_tid(wv) & 63, r32p = lp_ & 31, hip = lp_ >> 5;
;         exp_half(pA0);
;         ENDI();
; #pragma unroll 1
;         for (int j = 1; j + 1 < NT; j += 2) {
.Lsym_entry:
	v_mov_b32_e32 v0, 0
	v_mov_b32_e32 v1, 0
	v_mov_b32_e32 v2, 0
	v_mov_b32_e32 v3, 0
	v_mov_b32_e32 v4, 0
	v_mov_b32_e32 v5, 0
	v_mov_b32_e32 v6, 0
	v_mov_b32_e32 v7, 0
	v_mov_b32_e32 v8, 0
	v_mov_b32_e32 v9, 0
	v_mov_b32_e32 v10, 0
	v_mov_b32_e32 v11, 0
	v_mov_b32_e32 v12, 0
	v_mov_b32_e32 v13, 0
	v_mov_b32_e32 v14, 0
	v_mov_b32_e32 v15, 0
	v_mov_b32_e32 v16, 0
	v_mov_b32_e32 v17, 0
	v_mov_b32_e32 v18, 0
	v_mov_b32_e32 v19, 0
	v_mov_b32_e32 v20, 0
	v_mov_b32_e32 v21, 0
	v_mov_b32_e32 v22, 0
	v_mov_b32_e32 v23, 0
	v_mov_b32_e32 v24, 0
	v_mov_b32_e32 v25, 0
	v_mov_b32_e32 v26, 0
	v_mov_b32_e32 v27, 0
	v_mov_b32_e32 v28, 0
	v_mov_b32_e32 v29, 0
	v_mov_b32_e32 v30, 0
	v_mov_b32_e32 v31, 0
	v_mov_b32_e32 v32, 0
	v_mov_b32_e32 v33, 0
	v_mov_b32_e32 v34, 0
	v_mov_b32_e32 v35, 0
	v_mov_b32_e32 v36, 0
	v_mov_b32_e32 v37, 0
	v_mov_b32_e32 v38, 0
	v_mov_b32_e32 v39, 0
	v_mov_b32_e32 v40, 0
	v_mov_b32_e32 v41, 0
	v_mov_b32_e32 v42, 0
	v_mov_b32_e32 v43, 0
	v_mov_b32_e32 v44, 0
	v_mov_b32_e32 v45, 0
	v_mov_b32_e32 v46, 0
	v_mov_b32_e32 v47, 0
	v_mov_b32_e32 v48, 0
	v_mov_b32_e32 v49, 0
	v_mov_b32_e32 v50, 0
	v_mov_b32_e32 v51, 0
	v_mov_b32_e32 v52, 0
	v_mov_b32_e32 v53, 0
	v_mov_b32_e32 v54, 0
	v_mov_b32_e32 v55, 0
	v_mov_b32_e32 v56, 0
	v_mov_b32_e32 v57, 0
	v_mov_b32_e32 v58, 0
	v_mov_b32_e32 v59, 0
	v_mov_b32_e32 v60, 0
	v_mov_b32_e32 v61, 0
	v_mov_b32_e32 v62, 0
	v_mov_b32_e32 v63, 0
	v_mov_b32_e32 v182, 0
	v_mbcnt_lo_u32_b32 v190, -1, 0
	v_mbcnt_hi_u32_b32 v190, -1, v190
	v_and_b32_e32 v191, 31, v190
	v_lshrrev_b32_e32 v187, 5, v190
	v_lshlrev_b32_e32 v185, 4, v187
	v_or_b32_e32 v185, s52, v185
	v_and_b32_e32 v183, 15, v191
	v_lshlrev_b32_e32 v183, 4, v183
	v_xor_b32_e32 v185, v185, v183
	v_lshlrev_b32_e32 v183, 8, v191
	v_xor_b32_e32 v178, 0, v185
	v_add_u32_e32 v178, v178, v183
	v_add_u32_e32 v178, 0x10000, v178
	v_xor_b32_e32 v179, 32, v185
	v_add_u32_e32 v179, v179, v183
	v_add_u32_e32 v179, 0x10000, v179
	v_xor_b32_e32 v180, 64, v185
	v_add_u32_e32 v180, v180, v183
	v_add_u32_e32 v180, 0x10000, v180
	v_xor_b32_e32 v181, 96, v185
	v_add_u32_e32 v181, v181, v183
	v_add_u32_e32 v181, 0x10000, v181
	s_add_i32 s55, s63, 64
	v_subrev_u32_e32 v183, 64, v236
	v_cvt_f32_i32_e32 v183, v183
	s_mov_b32 s54, 0
	s_add_u32 s56, s20, 0x1c1e00
	s_addc_u32 s57, s21, 0
	v_exp_f32_e32 v80, v80
	v_exp_f32_e32 v81, v81
	v_exp_f32_e32 v82, v82
	v_exp_f32_e32 v83, v83
	v_add_f32_e32 v182, v80, v182
	v_add_f32_e32 v182, v81, v182
	v_cvt_pk_bf16_f32 v128, v80, v81
	v_exp_f32_e32 v84, v84
	v_exp_f32_e32 v85, v85
	v_add_f32_e32 v182, v82, v182
	v_add_f32_e32 v182, v83, v182
	v_cvt_pk_bf16_f32 v129, v82, v83
	v_exp_f32_e32 v86, v86
	v_exp_f32_e32 v87, v87
	v_add_f32_e32 v182, v84, v182
	v_add_f32_e32 v182, v85, v182
	v_cvt_pk_bf16_f32 v130, v84, v85
	v_cvt_pk_bf16_f32 v131, v86, v87
	v_add_f32_e32 v182, v86, v182
	v_add_f32_e32 v182, v87, v182
	.p2alignl 6, 3212836864

; template <class Epi, class Sched, bool ALIGN_EPI = false, bool SP2 = false>
; __device__ __forceinline__ void gemm_phase(PG8_LAS unsigned char* lds, const Gemm g, const Sched& S, const Epi& E, int wv) {
;     ...
;         const bool has_next = S.next(ui + 1, nxt);
;         const char* nA = has_next ? (const char*)g.A + (size_t)nxt.pm * tstep : cA; const char* nB = has_next ? (const char*)g.Bt + (size_t)nxt.pn * tstep : cB;
;         for (int t = 0; t < nt; t += 2) {
;             const bool last = (t == nt - 2);
;             const char* a1 = cA + (size_t)(t + 1) * kstep;
;             const char* a2 = last ? nA : cA + (size_t)(t + 2) * kstep; const char* b2 = last ? nB : cB + (size_t)(t + 2) * kstep;
;             const char* a3 = a2 + kstep; const char* b3 = b2 + kstep;
;     ...
; #pragma unroll
;         for (int a = 0; a < 2; ++a)
; #pragma unroll
;             for (int b = 0; b < 2; ++b)
; #pragma unroll
;                 for (int m = 0; m < 4; ++m)
; #pragma unroll
;                     for (int n = 0; n < 2; ++n) acc[a][b][m][n] = (f32x4){0.f, 0.f, 0.f, 0.f};
.LBB0_342:
	s_ashr_i32 s21, s20, 31
	s_lshl_b64 s[44:45], s[20:21], 20
	s_add_u32 s44, s82, s44
	s_addc_u32 s45, s83, s45
	s_and_b64 s[46:47], s[38:39], exec
	s_cselect_b32 s7, s45, s41
	s_cselect_b32 s21, s44, s40
	s_ashr_i32 s19, s18, 31
	s_lshl_b64 s[46:47], s[18:19], 20
	s_add_u32 s46, s0, s46
	s_addc_u32 s47, s1, s47
	s_and_b64 s[50:51], s[38:39], exec
	s_cselect_b32 s19, s47, s49
	s_cselect_b32 s35, s46, s48
	s_add_u32 s40, s40, 0x80080
	s_addc_u32 s41, s41, 0
	s_add_u32 s52, s48, 0x100
	v_mov_b32_e32 v0, 0
	s_addc_u32 s53, s49, 0
	s_mov_b32 s54, -2
	v_mov_b32_e32 v1, v0
	v_mov_b32_e32 v2, v0
	v_mov_b32_e32 v3, v0
	v_mov_b32_e32 v4, v0
	v_mov_b32_e32 v5, v0
	v_mov_b32_e32 v6, v0
	v_mov_b32_e32 v7, v0
	v_mov_b32_e32 v16, v0
	v_mov_b32_e32 v17, v0
	v_mov_b32_e32 v18, v0
	v_mov_b32_e32 v19, v0
	v_mov_b32_e32 v20, v0
	v_mov_b32_e32 v21, v0
	v_mov_b32_e32 v22, v0
	v_mov_b32_e32 v23, v0
	v_mov_b32_e32 v32, v0
	v_mov_b32_e32 v33, v0
	v_mov_b32_e32 v34, v0
	v_mov_b32_e32 v35, v0
	v_mov_b32_e32 v36, v0
	v_mov_b32_e32 v37, v0
	v_mov_b32_e32 v38, v0
	v_mov_b32_e32 v39, v0
	v_mov_b32_e32 v48, v0
	v_mov_b32_e32 v49, v0
	v_mov_b32_e32 v50, v0
	v_mov_b32_e32 v51, v0
	v_mov_b32_e32 v52, v0
	v_mov_b32_e32 v53, v0
	v_mov_b32_e32 v54, v0
	v_mov_b32_e32 v55, v0
	v_mov_b32_e32 v8, v0
	v_mov_b32_e32 v9, v0
	v_mov_b32_e32 v10, v0
	v_mov_b32_e32 v11, v0
	v_mov_b32_e32 v12, v0
	v_mov_b32_e32 v13, v0
	v_mov_b32_e32 v14, v0
	v_mov_b32_e32 v15, v0
	v_mov_b32_e32 v24, v0
	v_mov_b32_e32 v25, v0
	v_mov_b32_e32 v26, v0
	v_mov_b32_e32 v27, v0
	v_mov_b32_e32 v28, v0
	v_mov_b32_e32 v29, v0
	v_mov_b32_e32 v30, v0
	v_mov_b32_e32 v31, v0
	v_mov_b32_e32 v40, v0
	v_mov_b32_e32 v41, v0
	v_mov_b32_e32 v42, v0
	v_mov_b32_e32 v43, v0
	v_mov_b32_e32 v44, v0
	v_mov_b32_e32 v45, v0
	v_mov_b32_e32 v46, v0
	v_mov_b32_e32 v47, v0
	v_mov_b32_e32 v56, v0
	v_mov_b32_e32 v57, v0
	v_mov_b32_e32 v58, v0
	v_mov_b32_e32 v59, v0
	v_mov_b32_e32 v60, v0
	v_mov_b32_e32 v61, v0
	v_mov_b32_e32 v62, v0
	v_mov_b32_e32 v63, v0
	v_mov_b32_e32 v64, v0
	v_mov_b32_e32 v65, v0
	v_mov_b32_e32 v66, v0
	v_mov_b32_e32 v67, v0
	v_mov_b32_e32 v68, v0
	v_mov_b32_e32 v69, v0
	v_mov_b32_e32 v70, v0
	v_mov_b32_e32 v71, v0
	v_mov_b32_e32 v80, v0
	v_mov_b32_e32 v81, v0
	v_mov_b32_e32 v82, v0
	v_mov_b32_e32 v83, v0
	v_mov_b32_e32 v84, v0
	v_mov_b32_e32 v85, v0
	v_mov_b32_e32 v86, v0
	v_mov_b32_e32 v87, v0
	v_mov_b32_e32 v96, v0
	v_mov_b32_e32 v97, v0
	v_mov_b32_e32 v98, v0
	v_mov_b32_e32 v99, v0
	v_mov_b32_e32 v100, v0
	v_mov_b32_e32 v101, v0
	v_mov_b32_e32 v102, v0
	v_mov_b32_e32 v103, v0
	v_mov_b32_e32 v112, v0
	v_mov_b32_e32 v113, v0
	v_mov_b32_e32 v114, v0
	v_mov_b32_e32 v115, v0
	v_mov_b32_e32 v116, v0
	v_mov_b32_e32 v117, v0
	v_mov_b32_e32 v118, v0
	v_mov_b32_e32 v119, v0
	v_mov_b32_e32 v72, v0
	v_mov_b32_e32 v73, v0
	v_mov_b32_e32 v74, v0
	v_mov_b32_e32 v75, v0
	v_mov_b32_e32 v76, v0
	v_mov_b32_e32 v77, v0
	v_mov_b32_e32 v78, v0
	v_mov_b32_e32 v79, v0
	v_mov_b32_e32 v88, v0
	v_mov_b32_e32 v89, v0
	v_mov_b32_e32 v90, v0
	v_mov_b32_e32 v91, v0
	v_mov_b32_e32 v92, v0
	v_mov_b32_e32 v93, v0
	v_mov_b32_e32 v94, v0
	v_mov_b32_e32 v95, v0
	v_mov_b32_e32 v104, v0
	v_mov_b32_e32 v105, v0
	v_mov_b32_e32 v106, v0
	v_mov_b32_e32 v107, v0
	v_mov_b32_e32 v108, v0
	v_mov_b32_e32 v109, v0
	v_mov_b32_e32 v110, v0
	v_mov_b32_e32 v111, v0
	v_mov_b32_e32 v120, v0
	v_mov_b32_e32 v121, v0
	v_mov_b32_e32 v122, v0
	v_mov_b32_e32 v123, v0
	v_mov_b32_e32 v124, v0
	v_mov_b32_e32 v125, v0
	v_mov_b32_e32 v126, v0
	v_mov_b32_e32 v127, v0
	.p2alignl 6, 3212836864
